# scan phase rewritten by hand: all 8 waves scan 4 rows each, staging merged, one barrier per chunk
# baseline (speedup 1.0000x reference)
; #define GAS __attribute__((address_space(1)))
; __device__ __forceinline__ void rwkv_scan_phase(Frame& F, const bf16* RKV, const float* WAG, const bf16* AGB, const float* k_k, const float* k_a, const float* r_k, bf16* Y, float* BS, float* ST2) {
;     ...
;     for (int item = F.vcu; item < NB * 32 * 2; item += F.G) {
;         const int half = item & 1, h = (item >> 1) & 31, b = item >> 6;
;         const size_t gbase = (size_t)b * SEQ * D + h * 64;
;         __syncthreads();
;         if (wave >= 4) {
;             const int st = tid - 256, ts = st >> 4, c4 = st & 15;
;             const f32x4 kkc = *(const GAS f32x4*)(k_k + h * 64 + 4 * c4), kac = *(const GAS f32x4*)(k_a + h * 64 + 4 * c4), rkc = *(const GAS f32x4*)(r_k + h * 64 + 4 * c4);
.LBB0_1684:
	s_cmp_gt_i32 s56, 15
	s_cselect_b64 s[0:1], -1, 0
	s_cmp_lt_i32 s57, 16
	s_cselect_b64 s[4:5], -1, 0
	s_or_b64 s[0:1], s[0:1], s[4:5]
	s_and_b64 vcc, exec, s[0:1]
	s_cbranch_vccnz .LBB0_1868
	s_add_i32 s0, 0, 0x20520
	v_mov_b32_e32 v0, s0
	s_waitcnt lgkmcnt(0)
	ds_read_b64 v[4:5], v0
	s_add_i32 s0, 0, 0x20480
	v_mov_b32_e32 v0, s0
	ds_read_b128 v[6:9], v0
	s_add_i32 s0, 0, 0x20490
	v_mov_b32_e32 v0, s0
	ds_read_b64 v[10:11], v0
	s_waitcnt lgkmcnt(0)
	s_nop 0
	v_readfirstlane_b32 s10, v4
	v_readfirstlane_b32 s11, v5
	v_readfirstlane_b32 s6, v6
	v_readfirstlane_b32 s7, v7
	v_readfirstlane_b32 s8, v8
	v_readfirstlane_b32 s9, v9
	v_readfirstlane_b32 s24, v10
	v_readfirstlane_b32 s25, v11
	s_mov_b32 s33, s96
	s_cmpk_gt_i32 s96, 0xff
	s_cbranch_scc1 .LBB0_1814
	v_mbcnt_lo_u32_b32 v0, -1, 0
	v_mbcnt_hi_u32_b32 v0, -1, v0
	v_lshl_add_u32 v110, s80, 6, v0
	v_lshrrev_b32_e32 v111, 4, v110
	v_and_b32_e32 v112, 15, v0
	v_and_b32_e32 v109, 15, v0
	v_lshrrev_b32_e32 v113, 4, v0
	v_lshl_add_u32 v114, s80, 2, v113
	v_lshlrev_b32_e32 v102, 12, v111
	v_lshl_add_u32 v102, v112, 3, v102
	v_lshlrev_b32_e32 v103, 13, v111
	v_lshl_add_u32 v103, v112, 4, v103
	v_lshlrev_b32_e32 v104, 8, v111
	v_lshl_add_u32 v104, v112, 4, v104
	v_and_b32_e32 v115, 7, v112
	v_mul_u32_u24_e32 v106, 576, v115
	v_lshl_add_u32 v106, v111, 2, v106
	v_add_u32_e32 v106, 0xa000, v106
	v_lshlrev_b32_e32 v108, 7, v111
	v_lshlrev_b32_e32 v71, 4, v112
	v_mul_u32_u24_e32 v72, 144, v114
	v_add_u32_e32 v72, 0xa000, v72
	v_lshlrev_b32_e32 v116, 2, v114
	v_lshlrev_b32_e32 v117, 2, v0
	v_add_u32_e32 v117, 0x2000, v117
	v_cmp_eq_u32_e32 vcc, 0, v112
	s_nop 1
	v_cndmask_b32_e32 v73, v117, v116, vcc
	v_subrev_u32_e32 v118, 0x100, v110
	v_lshrrev_b32_e32 v119, 3, v118
	v_and_b32_e32 v120, 7, v118
	v_lshlrev_b32_e32 v160, 7, v119
	v_lshl_add_u32 v160, v120, 4, v160
	v_lshlrev_b32_e32 v162, 12, v119
	v_lshl_add_u32 v162, v120, 3, v162
	v_lshlrev_b32_e32 v163, 9, v119
	s_mov_b32 s46, 0x01010101
	s_mov_b32 s47, 0x01010101
.Lscan_item:
	s_and_b32 s34, s33, 1
	s_bfe_u32 s35, s33, 0x50001
	s_lshr_b32 s36, s33, 6
	s_lshl_b32 s0, s36, 23
	s_lshl_b32 s1, s35, 7
	s_add_u32 s0, s0, s1
	s_add_u32 s12, s10, 0x3c500000
	s_addc_u32 s13, s11, 0
	s_add_u32 s12, s12, s0
	s_addc_u32 s13, s13, 0
	s_add_u32 s26, s10, 0x3e500000
	s_addc_u32 s27, s11, 0
	s_add_u32 s26, s26, s0
	s_addc_u32 s27, s27, 0
	s_add_u32 s28, s10, 0x40500000
	s_addc_u32 s29, s11, 0
	s_add_u32 s28, s28, s0
	s_addc_u32 s29, s29, 0
	s_add_u32 s16, s10, 0x34500000
	s_addc_u32 s17, s11, 0
	s_add_u32 s16, s16, s0
	s_addc_u32 s17, s17, 0
	s_lshl_b32 s3, s0, 1
	s_add_u32 s14, s10, 0x30500000
	s_addc_u32 s15, s11, 0
	s_add_u32 s14, s14, s3
	s_addc_u32 s15, s15, 0
	s_lshl_b32 s4, s34, 6
	s_add_u32 s4, s4, s0
	s_add_u32 s18, s10, 0x49100000
	s_addc_u32 s19, s11, 0
	s_add_u32 s18, s18, s4
	s_addc_u32 s19, s19, 0
	s_lshl_b32 s3, s36, 18
	s_lshl_b32 s4, s35, 2
	s_add_u32 s3, s3, s4
	s_add_u32 s30, s10, 0x48500000
	s_addc_u32 s31, s11, 0
	s_add_u32 s30, s30, s3
	s_addc_u32 s31, s31, 0
	s_lshl_b32 s3, s36, 20
	s_lshl_b32 s4, s35, 4
	s_add_u32 s3, s3, s4
	s_lshl_b32 s4, s34, 3
	s_add_u32 s3, s3, s4
	s_add_u32 s20, s10, 0x48700000
	s_addc_u32 s21, s11, 0
	s_add_u32 s20, s20, s3
	s_addc_u32 s21, s21, 0
	s_cmp_eq_u32 s34, 0
	s_lshl_b32 s4, s34, 3
	s_lshl_b32 s42, 0x00ff00ff, s4
	s_cmp_eq_u32 s34, 0
	s_mov_b32 s43, s42
	s_cselect_b32 s44, 0x00010001, 0
	s_mov_b32 s45, s44
	s_lshl_b32 s1, s35, 8
	v_lshl_add_u32 v176, v109, 4, s1
	s_barrier
	global_load_dwordx4 v[86:89], v176, s[6:7]
	global_load_dwordx4 v[90:93], v176, s[8:9]
	global_load_dwordx4 v[98:101], v176, s[24:25]
	global_load_dwordx2 v[74:75], v102, s[12:13]
	global_load_dwordx2 v[76:77], v102, s[26:27]
	global_load_dwordx2 v[80:81], v102, s[16:17]
	global_load_dwordx4 v[82:85], v103, s[14:15]
	global_load_dwordx2 v[78:79], v102, s[28:29]
	s_mov_b32 s38, 0
	s_mov_b32 s39, 0
	s_mov_b32 s40, 0x16800
	s_mov_b32 s41, 0x17800
	s_waitcnt vmcnt(0)
	v_sub_f32_e32 v94, 1.0, v90
	v_sub_f32_e32 v95, 1.0, v91
	v_sub_f32_e32 v96, 1.0, v92
	v_sub_f32_e32 v97, 1.0, v93
	v_lshlrev_b32_e32 v110, 16, v74
	v_and_b32_e32 v111, 0xffff0000, v74
	v_lshlrev_b32_e32 v112, 16, v75
	v_and_b32_e32 v113, 0xffff0000, v75
	v_lshlrev_b32_e32 v114, 16, v76
	v_and_b32_e32 v115, 0xffff0000, v76
	v_lshlrev_b32_e32 v116, 16, v77
	v_and_b32_e32 v117, 0xffff0000, v77
	v_lshlrev_b32_e32 v118, 16, v80
	v_and_b32_e32 v119, 0xffff0000, v80
	v_lshlrev_b32_e32 v120, 16, v81
	v_and_b32_e32 v121, 0xffff0000, v81
	v_lshlrev_b32_e32 v122, 16, v78
	v_and_b32_e32 v123, 0xffff0000, v78
	v_lshlrev_b32_e32 v124, 16, v79
	v_and_b32_e32 v125, 0xffff0000, v79
	v_add_u32_e32 v105, s39, v104
	v_add_u32_e32 v107, s39, v106
	v_pk_mul_f32 v[126:127], v[114:115], v[86:87]
	v_pk_mul_f32 v[128:129], v[116:117], v[88:89]
	v_pk_fma_f32 v[150:151], v[118:119], v[90:91], v[94:95]
	v_pk_fma_f32 v[152:153], v[120:121], v[92:93], v[96:97]
	v_mul_f32_e32 v146, v126, v126
	v_mul_f32_e32 v147, v128, v128
	v_fmac_f32_e32 v146, v127, v127
	v_fmac_f32_e32 v147, v129, v129
	v_pk_mul_f32 v[130:131], v[114:115], v[150:151]
	v_pk_mul_f32 v[132:133], v[116:117], v[152:153]
	v_add_f32_e32 v146, v146, v147
	v_pk_mul_f32 v[142:143], v[110:111], v[130:131]
	v_pk_mul_f32 v[144:145], v[112:113], v[132:133]
	v_add_f32_dpp v146, v146, v146 quad_perm:[1,0,3,2] row_mask:0xf bank_mask:0xf bound_ctrl:1
	v_pk_mul_f32 v[142:143], v[142:143], v[98:99]
	v_pk_mul_f32 v[144:145], v[144:145], v[100:101]
	v_add_f32_dpp v146, v146, v146 quad_perm:[2,3,0,1] row_mask:0xf bank_mask:0xf bound_ctrl:1
	v_add_f32_e32 v154, v142, v143
	v_add_f32_e32 v147, v144, v145
; __device__ __forceinline__ void rwkv_scan_phase(Frame& F, const bf16* RKV, const float* WAG, const bf16* AGB, const float* k_k, const float* k_a, const float* r_k, bf16* Y, float* BS, float* ST2) {
;     ...
;             ST_LOAD(RA, 0); ST_LOAD(RB, 1);
;             ST_PROC(RA, 0);
;             __syncthreads();
;             for (int ci = 0; ci < NCH; ci += 2) {
;                 if (ci >= 1) ST_FLUSH(ci - 1);
;                 if (ci + 2 < NCH) ST_LOAD(RA, ci + 2);
;                 ST_PROC(RB, ci + 1);
;                 __syncthreads();
;                 ST_FLUSH(ci);
;                 if (ci + 3 < NCH) ST_LOAD(RB, ci + 3);
;                 if (ci + 2 < NCH) ST_PROC(RA, ci + 2);
;                 __syncthreads();
	v_add_f32_dpp v146, v146, v146 row_half_mirror row_mask:0xf bank_mask:0xf bound_ctrl:1
	v_add_f32_e32 v154, v154, v147
	ds_write_b128 v105, v[110:113] offset:0
	v_add_f32_dpp v146, v146, v146 row_mirror row_mask:0xf bank_mask:0xf bound_ctrl:1
	v_add_f32_dpp v154, v154, v154 quad_perm:[1,0,3,2] row_mask:0xf bank_mask:0xf bound_ctrl:1
	ds_write_b128 v105, v[82:85] offset:8192
	v_rsq_f32_e32 v148, v146
	v_add_f32_dpp v154, v154, v154 quad_perm:[2,3,0,1] row_mask:0xf bank_mask:0xf bound_ctrl:1
	ds_write_b128 v105, v[130:133] offset:16384
	v_min_f32_e32 v148, 0x5368d4a5, v148
	v_add_f32_dpp v154, v154, v154 row_half_mirror row_mask:0xf bank_mask:0xf bound_ctrl:1
	v_pk_mul_f32 v[134:135], v[126:127], v[148:149] op_sel_hi:[1,0] neg_lo:[0,1] neg_hi:[0,1]
	v_pk_mul_f32 v[136:137], v[128:129], v[148:149] op_sel_hi:[1,0] neg_lo:[0,1] neg_hi:[0,1]
	v_add_f32_dpp v154, v154, v154 row_mirror row_mask:0xf bank_mask:0xf bound_ctrl:1
	v_pk_mul_f32 v[138:139], v[134:135], v[118:119] neg_lo:[1,0] neg_hi:[1,0]
	v_pk_mul_f32 v[140:141], v[136:137], v[120:121] neg_lo:[1,0] neg_hi:[1,0]
	ds_write_b128 v105, v[134:137] offset:24576
	ds_write_b128 v105, v[138:141] offset:32768
	s_mov_b64 exec, s[42:43]
	s_nop 1
	ds_write2_b32 v107, v122, v123 offset0:0 offset1:36
	ds_write2_b32 v107, v124, v125 offset0:72 offset1:108
	s_mov_b64 exec, s[44:45]
	s_nop 1
	global_store_dword v108, v154, s[30:31]
	s_mov_b64 exec, -1
	s_nop 1
	s_add_u32 s30, s30, 0x1000
	s_addc_u32 s31, s31, 0
	s_add_u32 s12, s12, 0x20000
	s_addc_u32 s13, s13, 0
	s_add_u32 s26, s26, 0x20000
	s_addc_u32 s27, s27, 0
	s_add_u32 s28, s28, 0x20000
	s_addc_u32 s29, s29, 0
	s_add_u32 s16, s16, 0x20000
	s_addc_u32 s17, s17, 0
	s_add_u32 s14, s14, 0x40000
	s_addc_u32 s15, s15, 0
	global_load_dwordx2 v[74:75], v102, s[12:13]
	global_load_dwordx2 v[76:77], v102, s[26:27]
	global_load_dwordx2 v[80:81], v102, s[16:17]
	global_load_dwordx4 v[82:85], v103, s[14:15]
	global_load_dwordx2 v[78:79], v102, s[28:29]
	s_add_u32 s12, s12, 0x20000
	s_addc_u32 s13, s13, 0
	s_add_u32 s26, s26, 0x20000
	s_addc_u32 s27, s27, 0
	s_add_u32 s28, s28, 0x20000
	s_addc_u32 s29, s29, 0
	s_add_u32 s16, s16, 0x20000
	s_addc_u32 s17, s17, 0
	s_add_u32 s14, s14, 0x40000
	s_addc_u32 s15, s15, 0
	s_mov_b32 s39, 0xb400
	v_mov_b32_e32 v2, 0
	v_mov_b32_e32 v3, 0
	v_mov_b32_e32 v4, 0
	v_mov_b32_e32 v5, 0
	s_mov_b32 s37, 0
	s_waitcnt lgkmcnt(0)
	s_barrier
.Lscan_chunk:
	s_waitcnt vmcnt(0)
	s_cmp_ge_u32 s37, 63
	s_cbranch_scc1 .Lscan_nostage
	v_lshlrev_b32_e32 v110, 16, v74
	v_and_b32_e32 v111, 0xffff0000, v74
	v_lshlrev_b32_e32 v112, 16, v75
	v_and_b32_e32 v113, 0xffff0000, v75
	v_lshlrev_b32_e32 v114, 16, v76
	v_and_b32_e32 v115, 0xffff0000, v76
	v_lshlrev_b32_e32 v116, 16, v77
	v_and_b32_e32 v117, 0xffff0000, v77
	v_lshlrev_b32_e32 v118, 16, v80
	v_and_b32_e32 v119, 0xffff0000, v80
	v_lshlrev_b32_e32 v120, 16, v81
	v_and_b32_e32 v121, 0xffff0000, v81
	v_lshlrev_b32_e32 v122, 16, v78
	v_and_b32_e32 v123, 0xffff0000, v78
	v_lshlrev_b32_e32 v124, 16, v79
	v_and_b32_e32 v125, 0xffff0000, v79
	v_add_u32_e32 v105, s39, v104
	v_add_u32_e32 v107, s39, v106
	v_pk_mul_f32 v[126:127], v[114:115], v[86:87]
	v_pk_mul_f32 v[128:129], v[116:117], v[88:89]
	v_pk_fma_f32 v[150:151], v[118:119], v[90:91], v[94:95]
	v_pk_fma_f32 v[152:153], v[120:121], v[92:93], v[96:97]
	v_mul_f32_e32 v146, v126, v126
	v_mul_f32_e32 v147, v128, v128
	v_fmac_f32_e32 v146, v127, v127
	v_fmac_f32_e32 v147, v129, v129
	v_pk_mul_f32 v[130:131], v[114:115], v[150:151]
	v_pk_mul_f32 v[132:133], v[116:117], v[152:153]
	v_add_f32_e32 v146, v146, v147
	v_pk_mul_f32 v[142:143], v[110:111], v[130:131]
	v_pk_mul_f32 v[144:145], v[112:113], v[132:133]
	v_add_f32_dpp v146, v146, v146 quad_perm:[1,0,3,2] row_mask:0xf bank_mask:0xf bound_ctrl:1
	v_pk_mul_f32 v[142:143], v[142:143], v[98:99]
	v_pk_mul_f32 v[144:145], v[144:145], v[100:101]
	v_add_f32_dpp v146, v146, v146 quad_perm:[2,3,0,1] row_mask:0xf bank_mask:0xf bound_ctrl:1
	v_add_f32_e32 v154, v142, v143
	v_add_f32_e32 v147, v144, v145
	v_add_f32_dpp v146, v146, v146 row_half_mirror row_mask:0xf bank_mask:0xf bound_ctrl:1
	v_add_f32_e32 v154, v154, v147
	ds_write_b128 v105, v[110:113] offset:0
	v_add_f32_dpp v146, v146, v146 row_mirror row_mask:0xf bank_mask:0xf bound_ctrl:1
	v_add_f32_dpp v154, v154, v154 quad_perm:[1,0,3,2] row_mask:0xf bank_mask:0xf bound_ctrl:1
	ds_write_b128 v105, v[82:85] offset:8192
	v_rsq_f32_e32 v148, v146
	v_add_f32_dpp v154, v154, v154 quad_perm:[2,3,0,1] row_mask:0xf bank_mask:0xf bound_ctrl:1
	ds_write_b128 v105, v[130:133] offset:16384
	v_min_f32_e32 v148, 0x5368d4a5, v148
	v_add_f32_dpp v154, v154, v154 row_half_mirror row_mask:0xf bank_mask:0xf bound_ctrl:1
	v_pk_mul_f32 v[134:135], v[126:127], v[148:149] op_sel_hi:[1,0] neg_lo:[0,1] neg_hi:[0,1]
	v_pk_mul_f32 v[136:137], v[128:129], v[148:149] op_sel_hi:[1,0] neg_lo:[0,1] neg_hi:[0,1]
	v_add_f32_dpp v154, v154, v154 row_mirror row_mask:0xf bank_mask:0xf bound_ctrl:1
	v_pk_mul_f32 v[138:139], v[134:135], v[118:119] neg_lo:[1,0] neg_hi:[1,0]
	v_pk_mul_f32 v[140:141], v[136:137], v[120:121] neg_lo:[1,0] neg_hi:[1,0]
	ds_write_b128 v105, v[134:137] offset:24576
	ds_write_b128 v105, v[138:141] offset:32768
	s_mov_b64 exec, s[42:43]
	s_nop 1
	ds_write2_b32 v107, v122, v123 offset0:0 offset1:36
	ds_write2_b32 v107, v124, v125 offset0:72 offset1:108
	s_mov_b64 exec, s[44:45]
	s_nop 1
	global_store_dword v108, v154, s[30:31]
	s_mov_b64 exec, -1
	s_nop 1
	s_add_u32 s30, s30, 0x1000
	s_addc_u32 s31, s31, 0
	s_cmp_ge_u32 s37, 62
	s_cbranch_scc1 .Lscan_nostage
	global_load_dwordx2 v[74:75], v102, s[12:13]
	global_load_dwordx2 v[76:77], v102, s[26:27]
	global_load_dwordx2 v[80:81], v102, s[16:17]
	global_load_dwordx4 v[82:85], v103, s[14:15]
	global_load_dwordx2 v[78:79], v102, s[28:29]
	s_add_u32 s12, s12, 0x20000
	s_addc_u32 s13, s13, 0
	s_add_u32 s26, s26, 0x20000
	s_addc_u32 s27, s27, 0
	s_add_u32 s28, s28, 0x20000
	s_addc_u32 s29, s29, 0
	s_add_u32 s16, s16, 0x20000
	s_addc_u32 s17, s17, 0
	s_add_u32 s14, s14, 0x40000
	s_addc_u32 s15, s15, 0
; __device__ __forceinline__ void rwkv_scan_phase(Frame& F, const bf16* RKV, const float* WAG, const bf16* AGB, const float* k_k, const float* k_a, const float* r_k, bf16* Y, float* BS, float* ST2) {
;     ...
;                 f32x2 r0[4], w0[4], k0[4], a0[4], b0[4], r1[4], w1[4], k1[4], a1[4], b1[4]; float v0, v1;
;                 SC_LOAD(r0, w0, k0, a0, b0, v0, 0);
; #pragma unroll
;                 for (int t = 0; t < SC_T; t += 2) {
;                     SC_LOAD(r1, w1, k1, a1, b1, v1, t + 1);
;                     SC_STEP(r0, w0, k0, a0, b0, v0, t);
;                     if (t + 2 < SC_T) SC_LOAD(r0, w0, k0, a0, b0, v0, t + 2);
;                     SC_STEP(r1, w1, k1, a1, b1, v1, t + 1);
;                 }
.Lscan_nostage:
	s_cmp_lt_u32 s80, 4
	s_cbranch_scc1 .Lscan_noflush
	s_cmp_eq_u32 s37, 0
	s_cbranch_scc1 .Lscan_noflush
	v_add_u32_e32 v161, s41, v160
	ds_read_b128 v[164:167], v161
	s_waitcnt lgkmcnt(0)
	v_cvt_pk_bf16_f32 v168, v164, v165
	v_cvt_pk_bf16_f32 v169, v166, v167
	v_add_f32_e32 v170, v164, v165
	v_add_f32_e32 v172, v166, v167
	global_store_dwordx2 v162, v[168:169], s[18:19]
	v_mul_f32_e32 v171, v164, v164
	v_mul_f32_e32 v173, v166, v166
	v_add_f32_e32 v170, v170, v172
	v_fmac_f32_e32 v171, v165, v165
	v_fmac_f32_e32 v173, v167, v167
	v_add_f32_dpp v170, v170, v170 quad_perm:[1,0,3,2] row_mask:0xf bank_mask:0xf bound_ctrl:1
	v_add_f32_e32 v171, v171, v173
	s_nop 0
	v_add_f32_dpp v170, v170, v170 quad_perm:[2,3,0,1] row_mask:0xf bank_mask:0xf bound_ctrl:1
	v_add_f32_dpp v171, v171, v171 quad_perm:[1,0,3,2] row_mask:0xf bank_mask:0xf bound_ctrl:1
	s_nop 0
	v_add_f32_dpp v170, v170, v170 row_half_mirror row_mask:0xf bank_mask:0xf bound_ctrl:1
	v_add_f32_dpp v171, v171, v171 quad_perm:[2,3,0,1] row_mask:0xf bank_mask:0xf bound_ctrl:1
	s_nop 1
	v_add_f32_dpp v171, v171, v171 row_half_mirror row_mask:0xf bank_mask:0xf bound_ctrl:1
	s_mov_b64 exec, s[46:47]
	s_nop 1
	global_store_dwordx2 v163, v[170:171], s[20:21]
	s_mov_b64 exec, -1
	s_nop 1
	s_add_u32 s18, s18, 0x20000
	s_addc_u32 s19, s19, 0
	s_add_u32 s20, s20, 0x4000
	s_addc_u32 s21, s21, 0
.Lscan_noflush:
	v_add_u32_e32 v68, s38, v71
	v_add_u32_e32 v69, s38, v72
	v_add_u32_e32 v70, s40, v73
	ds_read_b128 v[32:35], v68 offset:24576
	ds_read_b128 v[24:27], v68 offset:8192
	ds_read_b128 v[28:31], v68 offset:16384
	ds_read_b128 v[36:39], v68 offset:32768
	ds_read_b128 v[20:23], v68 offset:0
	ds_read_b128 v[60:63], v69 offset:0
	ds_read_b128 v[52:55], v68 offset:24832
	ds_read_b128 v[44:47], v68 offset:8448
	ds_read_b128 v[48:51], v68 offset:16640
	ds_read_b128 v[56:59], v68 offset:33024
	ds_read_b128 v[40:43], v68 offset:256
	ds_read_b128 v[64:67], v69 offset:16
	s_waitcnt lgkmcnt(6)
	v_pk_mul_f32 v[6:7], v[2:3], v[32:33]
	v_pk_fma_f32 v[6:7], v[4:5], v[34:35], v[6:7]
	v_add_f32_e32 v14, v6, v7
	v_pk_mul_f32 v[8:9], v[2:3], v[24:25]
	s_nop 0
	v_add_f32_dpp v14, v14, v14 quad_perm:[1,0,3,2] row_mask:0xf bank_mask:0xf bound_ctrl:1
	v_pk_mul_f32 v[10:11], v[4:5], v[26:27]
	s_nop 0
	v_add_f32_dpp v14, v14, v14 quad_perm:[2,3,0,1] row_mask:0xf bank_mask:0xf bound_ctrl:1
	v_pk_fma_f32 v[8:9], v[28:29], v[60:61], v[8:9] op_sel_hi:[1,0,1]
	s_nop 0
	v_add_f32_dpp v14, v14, v14 row_half_mirror row_mask:0xf bank_mask:0xf bound_ctrl:1
	v_pk_fma_f32 v[10:11], v[30:31], v[60:61], v[10:11] op_sel_hi:[1,0,1]
	s_nop 0
	v_add_f32_dpp v14, v14, v14 row_mirror row_mask:0xf bank_mask:0xf bound_ctrl:1
	v_pk_fma_f32 v[2:3], v[36:37], v[14:15], v[8:9] op_sel_hi:[1,0,1]
	v_pk_fma_f32 v[4:5], v[38:39], v[14:15], v[10:11] op_sel_hi:[1,0,1]
	v_pk_mul_f32 v[12:13], v[2:3], v[20:21]
	v_pk_fma_f32 v[12:13], v[4:5], v[22:23], v[12:13]
	ds_read_b128 v[32:35], v68 offset:25088
	ds_read_b128 v[24:27], v68 offset:8704
	ds_read_b128 v[28:31], v68 offset:16896
	ds_read_b128 v[36:39], v68 offset:33280
	ds_read_b128 v[20:23], v68 offset:512
	s_waitcnt lgkmcnt(6)
	v_pk_mul_f32 v[6:7], v[2:3], v[52:53]
	v_pk_fma_f32 v[6:7], v[4:5], v[54:55], v[6:7]
	v_add_f32_e32 v16, v12, v13
	v_add_f32_e32 v14, v6, v7
	v_pk_mul_f32 v[8:9], v[2:3], v[44:45]
	v_add_f32_dpp v16, v16, v16 quad_perm:[1,0,3,2] row_mask:0xf bank_mask:0xf bound_ctrl:1
	v_add_f32_dpp v14, v14, v14 quad_perm:[1,0,3,2] row_mask:0xf bank_mask:0xf bound_ctrl:1
	v_pk_mul_f32 v[10:11], v[4:5], v[46:47]
	v_add_f32_dpp v16, v16, v16 quad_perm:[2,3,0,1] row_mask:0xf bank_mask:0xf bound_ctrl:1
	v_add_f32_dpp v14, v14, v14 quad_perm:[2,3,0,1] row_mask:0xf bank_mask:0xf bound_ctrl:1
	v_pk_fma_f32 v[8:9], v[48:49], v[60:61], v[8:9] op_sel:[0,1,0] op_sel_hi:[1,1,1]
	v_add_f32_dpp v16, v16, v16 row_half_mirror row_mask:0xf bank_mask:0xf bound_ctrl:1
	v_add_f32_dpp v14, v14, v14 row_half_mirror row_mask:0xf bank_mask:0xf bound_ctrl:1
	v_pk_fma_f32 v[10:11], v[50:51], v[60:61], v[10:11] op_sel:[0,1,0] op_sel_hi:[1,1,1]
	v_add_f32_dpp v16, v16, v16 row_mirror row_mask:0xf bank_mask:0xf bound_ctrl:1
	v_add_f32_dpp v14, v14, v14 row_mirror row_mask:0xf bank_mask:0xf bound_ctrl:1
	ds_write_b32 v70, v16 offset:0
	v_pk_fma_f32 v[2:3], v[56:57], v[14:15], v[8:9] op_sel_hi:[1,0,1]
	v_pk_fma_f32 v[4:5], v[58:59], v[14:15], v[10:11] op_sel_hi:[1,0,1]
	v_pk_mul_f32 v[12:13], v[2:3], v[40:41]
	v_pk_fma_f32 v[12:13], v[4:5], v[42:43], v[12:13]
	ds_read_b128 v[52:55], v68 offset:25344
	ds_read_b128 v[44:47], v68 offset:8960
	ds_read_b128 v[48:51], v68 offset:17152
	ds_read_b128 v[56:59], v68 offset:33536
	ds_read_b128 v[40:43], v68 offset:768
	s_waitcnt lgkmcnt(6)
	v_pk_mul_f32 v[6:7], v[2:3], v[32:33]
	v_pk_fma_f32 v[6:7], v[4:5], v[34:35], v[6:7]
	v_add_f32_e32 v16, v12, v13
	v_add_f32_e32 v14, v6, v7
	v_pk_mul_f32 v[8:9], v[2:3], v[24:25]
	v_add_f32_dpp v16, v16, v16 quad_perm:[1,0,3,2] row_mask:0xf bank_mask:0xf bound_ctrl:1
	v_add_f32_dpp v14, v14, v14 quad_perm:[1,0,3,2] row_mask:0xf bank_mask:0xf bound_ctrl:1
	v_pk_mul_f32 v[10:11], v[4:5], v[26:27]
	v_add_f32_dpp v16, v16, v16 quad_perm:[2,3,0,1] row_mask:0xf bank_mask:0xf bound_ctrl:1
	v_add_f32_dpp v14, v14, v14 quad_perm:[2,3,0,1] row_mask:0xf bank_mask:0xf bound_ctrl:1
	v_pk_fma_f32 v[8:9], v[28:29], v[62:63], v[8:9] op_sel_hi:[1,0,1]
	v_add_f32_dpp v16, v16, v16 row_half_mirror row_mask:0xf bank_mask:0xf bound_ctrl:1
	v_add_f32_dpp v14, v14, v14 row_half_mirror row_mask:0xf bank_mask:0xf bound_ctrl:1
	v_pk_fma_f32 v[10:11], v[30:31], v[62:63], v[10:11] op_sel_hi:[1,0,1]
	v_add_f32_dpp v16, v16, v16 row_mirror row_mask:0xf bank_mask:0xf bound_ctrl:1
	v_add_f32_dpp v14, v14, v14 row_mirror row_mask:0xf bank_mask:0xf bound_ctrl:1
	ds_write_b32 v70, v16 offset:128
	v_pk_fma_f32 v[2:3], v[36:37], v[14:15], v[8:9] op_sel_hi:[1,0,1]
	v_pk_fma_f32 v[4:5], v[38:39], v[14:15], v[10:11] op_sel_hi:[1,0,1]
	v_pk_mul_f32 v[12:13], v[2:3], v[20:21]
	v_pk_fma_f32 v[12:13], v[4:5], v[22:23], v[12:13]
	ds_read_b128 v[32:35], v68 offset:25600
	ds_read_b128 v[24:27], v68 offset:9216
	ds_read_b128 v[28:31], v68 offset:17408
	ds_read_b128 v[36:39], v68 offset:33792
	ds_read_b128 v[20:23], v68 offset:1024
	s_waitcnt lgkmcnt(6)
; __device__ __forceinline__ void rwkv_scan_phase(Frame& F, const bf16* RKV, const float* WAG, const bf16* AGB, const float* k_k, const float* k_a, const float* r_k, bf16* Y, float* BS, float* ST2) {
;     ...
;                 f32x2 r0[4], w0[4], k0[4], a0[4], b0[4], r1[4], w1[4], k1[4], a1[4], b1[4]; float v0, v1;
;                 SC_LOAD(r0, w0, k0, a0, b0, v0, 0);
; #pragma unroll
;                 for (int t = 0; t < SC_T; t += 2) {
;                     SC_LOAD(r1, w1, k1, a1, b1, v1, t + 1);
;                     SC_STEP(r0, w0, k0, a0, b0, v0, t);
;                     if (t + 2 < SC_T) SC_LOAD(r0, w0, k0, a0, b0, v0, t + 2);
;                     SC_STEP(r1, w1, k1, a1, b1, v1, t + 1);
;                 }
	v_pk_mul_f32 v[6:7], v[2:3], v[52:53]
	v_pk_fma_f32 v[6:7], v[4:5], v[54:55], v[6:7]
	v_add_f32_e32 v16, v12, v13
	v_add_f32_e32 v14, v6, v7
	v_pk_mul_f32 v[8:9], v[2:3], v[44:45]
	v_add_f32_dpp v16, v16, v16 quad_perm:[1,0,3,2] row_mask:0xf bank_mask:0xf bound_ctrl:1
	v_add_f32_dpp v14, v14, v14 quad_perm:[1,0,3,2] row_mask:0xf bank_mask:0xf bound_ctrl:1
	v_pk_mul_f32 v[10:11], v[4:5], v[46:47]
	v_add_f32_dpp v16, v16, v16 quad_perm:[2,3,0,1] row_mask:0xf bank_mask:0xf bound_ctrl:1
	v_add_f32_dpp v14, v14, v14 quad_perm:[2,3,0,1] row_mask:0xf bank_mask:0xf bound_ctrl:1
	v_pk_fma_f32 v[8:9], v[48:49], v[62:63], v[8:9] op_sel:[0,1,0] op_sel_hi:[1,1,1]
	v_add_f32_dpp v16, v16, v16 row_half_mirror row_mask:0xf bank_mask:0xf bound_ctrl:1
	v_add_f32_dpp v14, v14, v14 row_half_mirror row_mask:0xf bank_mask:0xf bound_ctrl:1
	v_pk_fma_f32 v[10:11], v[50:51], v[62:63], v[10:11] op_sel:[0,1,0] op_sel_hi:[1,1,1]
	v_add_f32_dpp v16, v16, v16 row_mirror row_mask:0xf bank_mask:0xf bound_ctrl:1
	v_add_f32_dpp v14, v14, v14 row_mirror row_mask:0xf bank_mask:0xf bound_ctrl:1
	ds_write_b32 v70, v16 offset:256
	v_pk_fma_f32 v[2:3], v[56:57], v[14:15], v[8:9] op_sel_hi:[1,0,1]
	v_pk_fma_f32 v[4:5], v[58:59], v[14:15], v[10:11] op_sel_hi:[1,0,1]
	v_pk_mul_f32 v[12:13], v[2:3], v[40:41]
	v_pk_fma_f32 v[12:13], v[4:5], v[42:43], v[12:13]
	ds_read_b128 v[52:55], v68 offset:25856
	ds_read_b128 v[44:47], v68 offset:9472
	ds_read_b128 v[48:51], v68 offset:17664
	ds_read_b128 v[56:59], v68 offset:34048
	ds_read_b128 v[40:43], v68 offset:1280
	ds_read_b128 v[60:63], v69 offset:32
	s_waitcnt lgkmcnt(7)
	v_pk_mul_f32 v[6:7], v[2:3], v[32:33]
	v_pk_fma_f32 v[6:7], v[4:5], v[34:35], v[6:7]
	v_add_f32_e32 v16, v12, v13
	v_add_f32_e32 v14, v6, v7
	v_pk_mul_f32 v[8:9], v[2:3], v[24:25]
	v_add_f32_dpp v16, v16, v16 quad_perm:[1,0,3,2] row_mask:0xf bank_mask:0xf bound_ctrl:1
	v_add_f32_dpp v14, v14, v14 quad_perm:[1,0,3,2] row_mask:0xf bank_mask:0xf bound_ctrl:1
	v_pk_mul_f32 v[10:11], v[4:5], v[26:27]
	v_add_f32_dpp v16, v16, v16 quad_perm:[2,3,0,1] row_mask:0xf bank_mask:0xf bound_ctrl:1
	v_add_f32_dpp v14, v14, v14 quad_perm:[2,3,0,1] row_mask:0xf bank_mask:0xf bound_ctrl:1
	v_pk_fma_f32 v[8:9], v[28:29], v[64:65], v[8:9] op_sel_hi:[1,0,1]
	v_add_f32_dpp v16, v16, v16 row_half_mirror row_mask:0xf bank_mask:0xf bound_ctrl:1
	v_add_f32_dpp v14, v14, v14 row_half_mirror row_mask:0xf bank_mask:0xf bound_ctrl:1
	v_pk_fma_f32 v[10:11], v[30:31], v[64:65], v[10:11] op_sel_hi:[1,0,1]
	v_add_f32_dpp v16, v16, v16 row_mirror row_mask:0xf bank_mask:0xf bound_ctrl:1
	v_add_f32_dpp v14, v14, v14 row_mirror row_mask:0xf bank_mask:0xf bound_ctrl:1
	ds_write_b32 v70, v16 offset:384
	v_pk_fma_f32 v[2:3], v[36:37], v[14:15], v[8:9] op_sel_hi:[1,0,1]
	v_pk_fma_f32 v[4:5], v[38:39], v[14:15], v[10:11] op_sel_hi:[1,0,1]
	v_pk_mul_f32 v[12:13], v[2:3], v[20:21]
	v_pk_fma_f32 v[12:13], v[4:5], v[22:23], v[12:13]
	ds_read_b128 v[32:35], v68 offset:26112
	ds_read_b128 v[24:27], v68 offset:9728
	ds_read_b128 v[28:31], v68 offset:17920
	ds_read_b128 v[36:39], v68 offset:34304
	ds_read_b128 v[20:23], v68 offset:1536
	s_waitcnt lgkmcnt(7)
	v_pk_mul_f32 v[6:7], v[2:3], v[52:53]
	v_pk_fma_f32 v[6:7], v[4:5], v[54:55], v[6:7]
	v_add_f32_e32 v16, v12, v13
	v_add_f32_e32 v14, v6, v7
	v_pk_mul_f32 v[8:9], v[2:3], v[44:45]
	v_add_f32_dpp v16, v16, v16 quad_perm:[1,0,3,2] row_mask:0xf bank_mask:0xf bound_ctrl:1
	v_add_f32_dpp v14, v14, v14 quad_perm:[1,0,3,2] row_mask:0xf bank_mask:0xf bound_ctrl:1
	v_pk_mul_f32 v[10:11], v[4:5], v[46:47]
	v_add_f32_dpp v16, v16, v16 quad_perm:[2,3,0,1] row_mask:0xf bank_mask:0xf bound_ctrl:1
	v_add_f32_dpp v14, v14, v14 quad_perm:[2,3,0,1] row_mask:0xf bank_mask:0xf bound_ctrl:1
	v_pk_fma_f32 v[8:9], v[48:49], v[64:65], v[8:9] op_sel:[0,1,0] op_sel_hi:[1,1,1]
	v_add_f32_dpp v16, v16, v16 row_half_mirror row_mask:0xf bank_mask:0xf bound_ctrl:1
	v_add_f32_dpp v14, v14, v14 row_half_mirror row_mask:0xf bank_mask:0xf bound_ctrl:1
	v_pk_fma_f32 v[10:11], v[50:51], v[64:65], v[10:11] op_sel:[0,1,0] op_sel_hi:[1,1,1]
	v_add_f32_dpp v16, v16, v16 row_mirror row_mask:0xf bank_mask:0xf bound_ctrl:1
	v_add_f32_dpp v14, v14, v14 row_mirror row_mask:0xf bank_mask:0xf bound_ctrl:1
	ds_write_b32 v70, v16 offset:512
	v_pk_fma_f32 v[2:3], v[56:57], v[14:15], v[8:9] op_sel_hi:[1,0,1]
	v_pk_fma_f32 v[4:5], v[58:59], v[14:15], v[10:11] op_sel_hi:[1,0,1]
	v_pk_mul_f32 v[12:13], v[2:3], v[40:41]
	v_pk_fma_f32 v[12:13], v[4:5], v[42:43], v[12:13]
	ds_read_b128 v[52:55], v68 offset:26368
	ds_read_b128 v[44:47], v68 offset:9984
	ds_read_b128 v[48:51], v68 offset:18176
	ds_read_b128 v[56:59], v68 offset:34560
	ds_read_b128 v[40:43], v68 offset:1792
	s_waitcnt lgkmcnt(6)
	v_pk_mul_f32 v[6:7], v[2:3], v[32:33]
	v_pk_fma_f32 v[6:7], v[4:5], v[34:35], v[6:7]
	v_add_f32_e32 v16, v12, v13
	v_add_f32_e32 v14, v6, v7
	v_pk_mul_f32 v[8:9], v[2:3], v[24:25]
	v_add_f32_dpp v16, v16, v16 quad_perm:[1,0,3,2] row_mask:0xf bank_mask:0xf bound_ctrl:1
	v_add_f32_dpp v14, v14, v14 quad_perm:[1,0,3,2] row_mask:0xf bank_mask:0xf bound_ctrl:1
	v_pk_mul_f32 v[10:11], v[4:5], v[26:27]
	v_add_f32_dpp v16, v16, v16 quad_perm:[2,3,0,1] row_mask:0xf bank_mask:0xf bound_ctrl:1
	v_add_f32_dpp v14, v14, v14 quad_perm:[2,3,0,1] row_mask:0xf bank_mask:0xf bound_ctrl:1
	v_pk_fma_f32 v[8:9], v[28:29], v[66:67], v[8:9] op_sel_hi:[1,0,1]
	v_add_f32_dpp v16, v16, v16 row_half_mirror row_mask:0xf bank_mask:0xf bound_ctrl:1
	v_add_f32_dpp v14, v14, v14 row_half_mirror row_mask:0xf bank_mask:0xf bound_ctrl:1
	v_pk_fma_f32 v[10:11], v[30:31], v[66:67], v[10:11] op_sel_hi:[1,0,1]
	v_add_f32_dpp v16, v16, v16 row_mirror row_mask:0xf bank_mask:0xf bound_ctrl:1
	v_add_f32_dpp v14, v14, v14 row_mirror row_mask:0xf bank_mask:0xf bound_ctrl:1
	ds_write_b32 v70, v16 offset:640
	v_pk_fma_f32 v[2:3], v[36:37], v[14:15], v[8:9] op_sel_hi:[1,0,1]
	v_pk_fma_f32 v[4:5], v[38:39], v[14:15], v[10:11] op_sel_hi:[1,0,1]
	v_pk_mul_f32 v[12:13], v[2:3], v[20:21]
	v_pk_fma_f32 v[12:13], v[4:5], v[22:23], v[12:13]
	ds_read_b128 v[32:35], v68 offset:26624
	ds_read_b128 v[24:27], v68 offset:10240
	ds_read_b128 v[28:31], v68 offset:18432
	ds_read_b128 v[36:39], v68 offset:34816
	ds_read_b128 v[20:23], v68 offset:2048
	s_waitcnt lgkmcnt(6)
; __device__ __forceinline__ void rwkv_scan_phase(Frame& F, const bf16* RKV, const float* WAG, const bf16* AGB, const float* k_k, const float* k_a, const float* r_k, bf16* Y, float* BS, float* ST2) {
;     ...
;                 f32x2 r0[4], w0[4], k0[4], a0[4], b0[4], r1[4], w1[4], k1[4], a1[4], b1[4]; float v0, v1;
;                 SC_LOAD(r0, w0, k0, a0, b0, v0, 0);
; #pragma unroll
;                 for (int t = 0; t < SC_T; t += 2) {
;                     SC_LOAD(r1, w1, k1, a1, b1, v1, t + 1);
;                     SC_STEP(r0, w0, k0, a0, b0, v0, t);
;                     if (t + 2 < SC_T) SC_LOAD(r0, w0, k0, a0, b0, v0, t + 2);
;                     SC_STEP(r1, w1, k1, a1, b1, v1, t + 1);
;                 }
	v_pk_mul_f32 v[6:7], v[2:3], v[52:53]
	v_pk_fma_f32 v[6:7], v[4:5], v[54:55], v[6:7]
	v_add_f32_e32 v16, v12, v13
	v_add_f32_e32 v14, v6, v7
	v_pk_mul_f32 v[8:9], v[2:3], v[44:45]
	v_add_f32_dpp v16, v16, v16 quad_perm:[1,0,3,2] row_mask:0xf bank_mask:0xf bound_ctrl:1
	v_add_f32_dpp v14, v14, v14 quad_perm:[1,0,3,2] row_mask:0xf bank_mask:0xf bound_ctrl:1
	v_pk_mul_f32 v[10:11], v[4:5], v[46:47]
	v_add_f32_dpp v16, v16, v16 quad_perm:[2,3,0,1] row_mask:0xf bank_mask:0xf bound_ctrl:1
	v_add_f32_dpp v14, v14, v14 quad_perm:[2,3,0,1] row_mask:0xf bank_mask:0xf bound_ctrl:1
	v_pk_fma_f32 v[8:9], v[48:49], v[66:67], v[8:9] op_sel:[0,1,0] op_sel_hi:[1,1,1]
	v_add_f32_dpp v16, v16, v16 row_half_mirror row_mask:0xf bank_mask:0xf bound_ctrl:1
	v_add_f32_dpp v14, v14, v14 row_half_mirror row_mask:0xf bank_mask:0xf bound_ctrl:1
	v_pk_fma_f32 v[10:11], v[50:51], v[66:67], v[10:11] op_sel:[0,1,0] op_sel_hi:[1,1,1]
	v_add_f32_dpp v16, v16, v16 row_mirror row_mask:0xf bank_mask:0xf bound_ctrl:1
	v_add_f32_dpp v14, v14, v14 row_mirror row_mask:0xf bank_mask:0xf bound_ctrl:1
	ds_write_b32 v70, v16 offset:768
	v_pk_fma_f32 v[2:3], v[56:57], v[14:15], v[8:9] op_sel_hi:[1,0,1]
	v_pk_fma_f32 v[4:5], v[58:59], v[14:15], v[10:11] op_sel_hi:[1,0,1]
	v_pk_mul_f32 v[12:13], v[2:3], v[40:41]
	v_pk_fma_f32 v[12:13], v[4:5], v[42:43], v[12:13]
	ds_read_b128 v[52:55], v68 offset:26880
	ds_read_b128 v[44:47], v68 offset:10496
	ds_read_b128 v[48:51], v68 offset:18688
	ds_read_b128 v[56:59], v68 offset:35072
	ds_read_b128 v[40:43], v68 offset:2304
	ds_read_b128 v[64:67], v69 offset:48
	s_waitcnt lgkmcnt(7)
	v_pk_mul_f32 v[6:7], v[2:3], v[32:33]
	v_pk_fma_f32 v[6:7], v[4:5], v[34:35], v[6:7]
	v_add_f32_e32 v16, v12, v13
	v_add_f32_e32 v14, v6, v7
	v_pk_mul_f32 v[8:9], v[2:3], v[24:25]
	v_add_f32_dpp v16, v16, v16 quad_perm:[1,0,3,2] row_mask:0xf bank_mask:0xf bound_ctrl:1
	v_add_f32_dpp v14, v14, v14 quad_perm:[1,0,3,2] row_mask:0xf bank_mask:0xf bound_ctrl:1
	v_pk_mul_f32 v[10:11], v[4:5], v[26:27]
	v_add_f32_dpp v16, v16, v16 quad_perm:[2,3,0,1] row_mask:0xf bank_mask:0xf bound_ctrl:1
	v_add_f32_dpp v14, v14, v14 quad_perm:[2,3,0,1] row_mask:0xf bank_mask:0xf bound_ctrl:1
	v_pk_fma_f32 v[8:9], v[28:29], v[60:61], v[8:9] op_sel_hi:[1,0,1]
	v_add_f32_dpp v16, v16, v16 row_half_mirror row_mask:0xf bank_mask:0xf bound_ctrl:1
	v_add_f32_dpp v14, v14, v14 row_half_mirror row_mask:0xf bank_mask:0xf bound_ctrl:1
	v_pk_fma_f32 v[10:11], v[30:31], v[60:61], v[10:11] op_sel_hi:[1,0,1]
	v_add_f32_dpp v16, v16, v16 row_mirror row_mask:0xf bank_mask:0xf bound_ctrl:1
	v_add_f32_dpp v14, v14, v14 row_mirror row_mask:0xf bank_mask:0xf bound_ctrl:1
	ds_write_b32 v70, v16 offset:896
	v_pk_fma_f32 v[2:3], v[36:37], v[14:15], v[8:9] op_sel_hi:[1,0,1]
	v_pk_fma_f32 v[4:5], v[38:39], v[14:15], v[10:11] op_sel_hi:[1,0,1]
	v_pk_mul_f32 v[12:13], v[2:3], v[20:21]
	v_pk_fma_f32 v[12:13], v[4:5], v[22:23], v[12:13]
	ds_read_b128 v[32:35], v68 offset:27136
	ds_read_b128 v[24:27], v68 offset:10752
	ds_read_b128 v[28:31], v68 offset:18944
	ds_read_b128 v[36:39], v68 offset:35328
	ds_read_b128 v[20:23], v68 offset:2560
	s_waitcnt lgkmcnt(7)
	v_pk_mul_f32 v[6:7], v[2:3], v[52:53]
	v_pk_fma_f32 v[6:7], v[4:5], v[54:55], v[6:7]
	v_add_f32_e32 v16, v12, v13
	v_add_f32_e32 v14, v6, v7
	v_pk_mul_f32 v[8:9], v[2:3], v[44:45]
	v_add_f32_dpp v16, v16, v16 quad_perm:[1,0,3,2] row_mask:0xf bank_mask:0xf bound_ctrl:1
	v_add_f32_dpp v14, v14, v14 quad_perm:[1,0,3,2] row_mask:0xf bank_mask:0xf bound_ctrl:1
	v_pk_mul_f32 v[10:11], v[4:5], v[46:47]
	v_add_f32_dpp v16, v16, v16 quad_perm:[2,3,0,1] row_mask:0xf bank_mask:0xf bound_ctrl:1
	v_add_f32_dpp v14, v14, v14 quad_perm:[2,3,0,1] row_mask:0xf bank_mask:0xf bound_ctrl:1
	v_pk_fma_f32 v[8:9], v[48:49], v[60:61], v[8:9] op_sel:[0,1,0] op_sel_hi:[1,1,1]
	v_add_f32_dpp v16, v16, v16 row_half_mirror row_mask:0xf bank_mask:0xf bound_ctrl:1
	v_add_f32_dpp v14, v14, v14 row_half_mirror row_mask:0xf bank_mask:0xf bound_ctrl:1
	v_pk_fma_f32 v[10:11], v[50:51], v[60:61], v[10:11] op_sel:[0,1,0] op_sel_hi:[1,1,1]
	v_add_f32_dpp v16, v16, v16 row_mirror row_mask:0xf bank_mask:0xf bound_ctrl:1
	v_add_f32_dpp v14, v14, v14 row_mirror row_mask:0xf bank_mask:0xf bound_ctrl:1
	ds_write_b32 v70, v16 offset:1024
	v_pk_fma_f32 v[2:3], v[56:57], v[14:15], v[8:9] op_sel_hi:[1,0,1]
	v_pk_fma_f32 v[4:5], v[58:59], v[14:15], v[10:11] op_sel_hi:[1,0,1]
	v_pk_mul_f32 v[12:13], v[2:3], v[40:41]
	v_pk_fma_f32 v[12:13], v[4:5], v[42:43], v[12:13]
	ds_read_b128 v[52:55], v68 offset:27392
	ds_read_b128 v[44:47], v68 offset:11008
	ds_read_b128 v[48:51], v68 offset:19200
	ds_read_b128 v[56:59], v68 offset:35584
	ds_read_b128 v[40:43], v68 offset:2816
	s_waitcnt lgkmcnt(6)
	v_pk_mul_f32 v[6:7], v[2:3], v[32:33]
	v_pk_fma_f32 v[6:7], v[4:5], v[34:35], v[6:7]
	v_add_f32_e32 v16, v12, v13
	v_add_f32_e32 v14, v6, v7
	v_pk_mul_f32 v[8:9], v[2:3], v[24:25]
	v_add_f32_dpp v16, v16, v16 quad_perm:[1,0,3,2] row_mask:0xf bank_mask:0xf bound_ctrl:1
	v_add_f32_dpp v14, v14, v14 quad_perm:[1,0,3,2] row_mask:0xf bank_mask:0xf bound_ctrl:1
	v_pk_mul_f32 v[10:11], v[4:5], v[26:27]
	v_add_f32_dpp v16, v16, v16 quad_perm:[2,3,0,1] row_mask:0xf bank_mask:0xf bound_ctrl:1
	v_add_f32_dpp v14, v14, v14 quad_perm:[2,3,0,1] row_mask:0xf bank_mask:0xf bound_ctrl:1
	v_pk_fma_f32 v[8:9], v[28:29], v[62:63], v[8:9] op_sel_hi:[1,0,1]
	v_add_f32_dpp v16, v16, v16 row_half_mirror row_mask:0xf bank_mask:0xf bound_ctrl:1
	v_add_f32_dpp v14, v14, v14 row_half_mirror row_mask:0xf bank_mask:0xf bound_ctrl:1
	v_pk_fma_f32 v[10:11], v[30:31], v[62:63], v[10:11] op_sel_hi:[1,0,1]
	v_add_f32_dpp v16, v16, v16 row_mirror row_mask:0xf bank_mask:0xf bound_ctrl:1
	v_add_f32_dpp v14, v14, v14 row_mirror row_mask:0xf bank_mask:0xf bound_ctrl:1
	ds_write_b32 v70, v16 offset:1152
	v_pk_fma_f32 v[2:3], v[36:37], v[14:15], v[8:9] op_sel_hi:[1,0,1]
	v_pk_fma_f32 v[4:5], v[38:39], v[14:15], v[10:11] op_sel_hi:[1,0,1]
	v_pk_mul_f32 v[12:13], v[2:3], v[20:21]
	v_pk_fma_f32 v[12:13], v[4:5], v[22:23], v[12:13]
	ds_read_b128 v[32:35], v68 offset:27648
	ds_read_b128 v[24:27], v68 offset:11264
	ds_read_b128 v[28:31], v68 offset:19456
	ds_read_b128 v[36:39], v68 offset:35840
	ds_read_b128 v[20:23], v68 offset:3072
	s_waitcnt lgkmcnt(6)
; __device__ __forceinline__ void rwkv_scan_phase(Frame& F, const bf16* RKV, const float* WAG, const bf16* AGB, const float* k_k, const float* k_a, const float* r_k, bf16* Y, float* BS, float* ST2) {
;     ...
;                 f32x2 r0[4], w0[4], k0[4], a0[4], b0[4], r1[4], w1[4], k1[4], a1[4], b1[4]; float v0, v1;
;                 SC_LOAD(r0, w0, k0, a0, b0, v0, 0);
; #pragma unroll
;                 for (int t = 0; t < SC_T; t += 2) {
;                     SC_LOAD(r1, w1, k1, a1, b1, v1, t + 1);
;                     SC_STEP(r0, w0, k0, a0, b0, v0, t);
;                     if (t + 2 < SC_T) SC_LOAD(r0, w0, k0, a0, b0, v0, t + 2);
;                     SC_STEP(r1, w1, k1, a1, b1, v1, t + 1);
;                 }
	v_pk_mul_f32 v[6:7], v[2:3], v[52:53]
	v_pk_fma_f32 v[6:7], v[4:5], v[54:55], v[6:7]
	v_add_f32_e32 v16, v12, v13
	v_add_f32_e32 v14, v6, v7
	v_pk_mul_f32 v[8:9], v[2:3], v[44:45]
	v_add_f32_dpp v16, v16, v16 quad_perm:[1,0,3,2] row_mask:0xf bank_mask:0xf bound_ctrl:1
	v_add_f32_dpp v14, v14, v14 quad_perm:[1,0,3,2] row_mask:0xf bank_mask:0xf bound_ctrl:1
	v_pk_mul_f32 v[10:11], v[4:5], v[46:47]
	v_add_f32_dpp v16, v16, v16 quad_perm:[2,3,0,1] row_mask:0xf bank_mask:0xf bound_ctrl:1
	v_add_f32_dpp v14, v14, v14 quad_perm:[2,3,0,1] row_mask:0xf bank_mask:0xf bound_ctrl:1
	v_pk_fma_f32 v[8:9], v[48:49], v[62:63], v[8:9] op_sel:[0,1,0] op_sel_hi:[1,1,1]
	v_add_f32_dpp v16, v16, v16 row_half_mirror row_mask:0xf bank_mask:0xf bound_ctrl:1
	v_add_f32_dpp v14, v14, v14 row_half_mirror row_mask:0xf bank_mask:0xf bound_ctrl:1
	v_pk_fma_f32 v[10:11], v[50:51], v[62:63], v[10:11] op_sel:[0,1,0] op_sel_hi:[1,1,1]
	v_add_f32_dpp v16, v16, v16 row_mirror row_mask:0xf bank_mask:0xf bound_ctrl:1
	v_add_f32_dpp v14, v14, v14 row_mirror row_mask:0xf bank_mask:0xf bound_ctrl:1
	ds_write_b32 v70, v16 offset:1280
	v_pk_fma_f32 v[2:3], v[56:57], v[14:15], v[8:9] op_sel_hi:[1,0,1]
	v_pk_fma_f32 v[4:5], v[58:59], v[14:15], v[10:11] op_sel_hi:[1,0,1]
	v_pk_mul_f32 v[12:13], v[2:3], v[40:41]
	v_pk_fma_f32 v[12:13], v[4:5], v[42:43], v[12:13]
	ds_read_b128 v[52:55], v68 offset:27904
	ds_read_b128 v[44:47], v68 offset:11520
	ds_read_b128 v[48:51], v68 offset:19712
	ds_read_b128 v[56:59], v68 offset:36096
	ds_read_b128 v[40:43], v68 offset:3328
	ds_read_b128 v[60:63], v69 offset:64
	s_waitcnt lgkmcnt(7)
	v_pk_mul_f32 v[6:7], v[2:3], v[32:33]
	v_pk_fma_f32 v[6:7], v[4:5], v[34:35], v[6:7]
	v_add_f32_e32 v16, v12, v13
	v_add_f32_e32 v14, v6, v7
	v_pk_mul_f32 v[8:9], v[2:3], v[24:25]
	v_add_f32_dpp v16, v16, v16 quad_perm:[1,0,3,2] row_mask:0xf bank_mask:0xf bound_ctrl:1
	v_add_f32_dpp v14, v14, v14 quad_perm:[1,0,3,2] row_mask:0xf bank_mask:0xf bound_ctrl:1
	v_pk_mul_f32 v[10:11], v[4:5], v[26:27]
	v_add_f32_dpp v16, v16, v16 quad_perm:[2,3,0,1] row_mask:0xf bank_mask:0xf bound_ctrl:1
	v_add_f32_dpp v14, v14, v14 quad_perm:[2,3,0,1] row_mask:0xf bank_mask:0xf bound_ctrl:1
	v_pk_fma_f32 v[8:9], v[28:29], v[64:65], v[8:9] op_sel_hi:[1,0,1]
	v_add_f32_dpp v16, v16, v16 row_half_mirror row_mask:0xf bank_mask:0xf bound_ctrl:1
	v_add_f32_dpp v14, v14, v14 row_half_mirror row_mask:0xf bank_mask:0xf bound_ctrl:1
	v_pk_fma_f32 v[10:11], v[30:31], v[64:65], v[10:11] op_sel_hi:[1,0,1]
	v_add_f32_dpp v16, v16, v16 row_mirror row_mask:0xf bank_mask:0xf bound_ctrl:1
	v_add_f32_dpp v14, v14, v14 row_mirror row_mask:0xf bank_mask:0xf bound_ctrl:1
	ds_write_b32 v70, v16 offset:1408
	v_pk_fma_f32 v[2:3], v[36:37], v[14:15], v[8:9] op_sel_hi:[1,0,1]
	v_pk_fma_f32 v[4:5], v[38:39], v[14:15], v[10:11] op_sel_hi:[1,0,1]
	v_pk_mul_f32 v[12:13], v[2:3], v[20:21]
	v_pk_fma_f32 v[12:13], v[4:5], v[22:23], v[12:13]
	ds_read_b128 v[32:35], v68 offset:28160
	ds_read_b128 v[24:27], v68 offset:11776
	ds_read_b128 v[28:31], v68 offset:19968
	ds_read_b128 v[36:39], v68 offset:36352
	ds_read_b128 v[20:23], v68 offset:3584
	s_waitcnt lgkmcnt(7)
	v_pk_mul_f32 v[6:7], v[2:3], v[52:53]
	v_pk_fma_f32 v[6:7], v[4:5], v[54:55], v[6:7]
	v_add_f32_e32 v16, v12, v13
	v_add_f32_e32 v14, v6, v7
	v_pk_mul_f32 v[8:9], v[2:3], v[44:45]
	v_add_f32_dpp v16, v16, v16 quad_perm:[1,0,3,2] row_mask:0xf bank_mask:0xf bound_ctrl:1
	v_add_f32_dpp v14, v14, v14 quad_perm:[1,0,3,2] row_mask:0xf bank_mask:0xf bound_ctrl:1
	v_pk_mul_f32 v[10:11], v[4:5], v[46:47]
	v_add_f32_dpp v16, v16, v16 quad_perm:[2,3,0,1] row_mask:0xf bank_mask:0xf bound_ctrl:1
	v_add_f32_dpp v14, v14, v14 quad_perm:[2,3,0,1] row_mask:0xf bank_mask:0xf bound_ctrl:1
	v_pk_fma_f32 v[8:9], v[48:49], v[64:65], v[8:9] op_sel:[0,1,0] op_sel_hi:[1,1,1]
	v_add_f32_dpp v16, v16, v16 row_half_mirror row_mask:0xf bank_mask:0xf bound_ctrl:1
	v_add_f32_dpp v14, v14, v14 row_half_mirror row_mask:0xf bank_mask:0xf bound_ctrl:1
	v_pk_fma_f32 v[10:11], v[50:51], v[64:65], v[10:11] op_sel:[0,1,0] op_sel_hi:[1,1,1]
	v_add_f32_dpp v16, v16, v16 row_mirror row_mask:0xf bank_mask:0xf bound_ctrl:1
	v_add_f32_dpp v14, v14, v14 row_mirror row_mask:0xf bank_mask:0xf bound_ctrl:1
	ds_write_b32 v70, v16 offset:1536
	v_pk_fma_f32 v[2:3], v[56:57], v[14:15], v[8:9] op_sel_hi:[1,0,1]
	v_pk_fma_f32 v[4:5], v[58:59], v[14:15], v[10:11] op_sel_hi:[1,0,1]
	v_pk_mul_f32 v[12:13], v[2:3], v[40:41]
	v_pk_fma_f32 v[12:13], v[4:5], v[42:43], v[12:13]
	ds_read_b128 v[52:55], v68 offset:28416
	ds_read_b128 v[44:47], v68 offset:12032
	ds_read_b128 v[48:51], v68 offset:20224
	ds_read_b128 v[56:59], v68 offset:36608
	ds_read_b128 v[40:43], v68 offset:3840
	s_waitcnt lgkmcnt(6)
	v_pk_mul_f32 v[6:7], v[2:3], v[32:33]
	v_pk_fma_f32 v[6:7], v[4:5], v[34:35], v[6:7]
	v_add_f32_e32 v16, v12, v13
	v_add_f32_e32 v14, v6, v7
	v_pk_mul_f32 v[8:9], v[2:3], v[24:25]
	v_add_f32_dpp v16, v16, v16 quad_perm:[1,0,3,2] row_mask:0xf bank_mask:0xf bound_ctrl:1
	v_add_f32_dpp v14, v14, v14 quad_perm:[1,0,3,2] row_mask:0xf bank_mask:0xf bound_ctrl:1
	v_pk_mul_f32 v[10:11], v[4:5], v[26:27]
	v_add_f32_dpp v16, v16, v16 quad_perm:[2,3,0,1] row_mask:0xf bank_mask:0xf bound_ctrl:1
	v_add_f32_dpp v14, v14, v14 quad_perm:[2,3,0,1] row_mask:0xf bank_mask:0xf bound_ctrl:1
	v_pk_fma_f32 v[8:9], v[28:29], v[66:67], v[8:9] op_sel_hi:[1,0,1]
	v_add_f32_dpp v16, v16, v16 row_half_mirror row_mask:0xf bank_mask:0xf bound_ctrl:1
	v_add_f32_dpp v14, v14, v14 row_half_mirror row_mask:0xf bank_mask:0xf bound_ctrl:1
	v_pk_fma_f32 v[10:11], v[30:31], v[66:67], v[10:11] op_sel_hi:[1,0,1]
	v_add_f32_dpp v16, v16, v16 row_mirror row_mask:0xf bank_mask:0xf bound_ctrl:1
	v_add_f32_dpp v14, v14, v14 row_mirror row_mask:0xf bank_mask:0xf bound_ctrl:1
	ds_write_b32 v70, v16 offset:1664
	v_pk_fma_f32 v[2:3], v[36:37], v[14:15], v[8:9] op_sel_hi:[1,0,1]
	v_pk_fma_f32 v[4:5], v[38:39], v[14:15], v[10:11] op_sel_hi:[1,0,1]
	v_pk_mul_f32 v[12:13], v[2:3], v[20:21]
	v_pk_fma_f32 v[12:13], v[4:5], v[22:23], v[12:13]
	ds_read_b128 v[32:35], v68 offset:28672
	ds_read_b128 v[24:27], v68 offset:12288
	ds_read_b128 v[28:31], v68 offset:20480
	ds_read_b128 v[36:39], v68 offset:36864
	ds_read_b128 v[20:23], v68 offset:4096
	s_waitcnt lgkmcnt(6)
; __device__ __forceinline__ void rwkv_scan_phase(Frame& F, const bf16* RKV, const float* WAG, const bf16* AGB, const float* k_k, const float* k_a, const float* r_k, bf16* Y, float* BS, float* ST2) {
;     ...
;                 f32x2 r0[4], w0[4], k0[4], a0[4], b0[4], r1[4], w1[4], k1[4], a1[4], b1[4]; float v0, v1;
;                 SC_LOAD(r0, w0, k0, a0, b0, v0, 0);
; #pragma unroll
;                 for (int t = 0; t < SC_T; t += 2) {
;                     SC_LOAD(r1, w1, k1, a1, b1, v1, t + 1);
;                     SC_STEP(r0, w0, k0, a0, b0, v0, t);
;                     if (t + 2 < SC_T) SC_LOAD(r0, w0, k0, a0, b0, v0, t + 2);
;                     SC_STEP(r1, w1, k1, a1, b1, v1, t + 1);
;                 }
	v_pk_mul_f32 v[6:7], v[2:3], v[52:53]
	v_pk_fma_f32 v[6:7], v[4:5], v[54:55], v[6:7]
	v_add_f32_e32 v16, v12, v13
	v_add_f32_e32 v14, v6, v7
	v_pk_mul_f32 v[8:9], v[2:3], v[44:45]
	v_add_f32_dpp v16, v16, v16 quad_perm:[1,0,3,2] row_mask:0xf bank_mask:0xf bound_ctrl:1
	v_add_f32_dpp v14, v14, v14 quad_perm:[1,0,3,2] row_mask:0xf bank_mask:0xf bound_ctrl:1
	v_pk_mul_f32 v[10:11], v[4:5], v[46:47]
	v_add_f32_dpp v16, v16, v16 quad_perm:[2,3,0,1] row_mask:0xf bank_mask:0xf bound_ctrl:1
	v_add_f32_dpp v14, v14, v14 quad_perm:[2,3,0,1] row_mask:0xf bank_mask:0xf bound_ctrl:1
	v_pk_fma_f32 v[8:9], v[48:49], v[66:67], v[8:9] op_sel:[0,1,0] op_sel_hi:[1,1,1]
	v_add_f32_dpp v16, v16, v16 row_half_mirror row_mask:0xf bank_mask:0xf bound_ctrl:1
	v_add_f32_dpp v14, v14, v14 row_half_mirror row_mask:0xf bank_mask:0xf bound_ctrl:1
	v_pk_fma_f32 v[10:11], v[50:51], v[66:67], v[10:11] op_sel:[0,1,0] op_sel_hi:[1,1,1]
	v_add_f32_dpp v16, v16, v16 row_mirror row_mask:0xf bank_mask:0xf bound_ctrl:1
	v_add_f32_dpp v14, v14, v14 row_mirror row_mask:0xf bank_mask:0xf bound_ctrl:1
	ds_write_b32 v70, v16 offset:1792
	v_pk_fma_f32 v[2:3], v[56:57], v[14:15], v[8:9] op_sel_hi:[1,0,1]
	v_pk_fma_f32 v[4:5], v[58:59], v[14:15], v[10:11] op_sel_hi:[1,0,1]
	v_pk_mul_f32 v[12:13], v[2:3], v[40:41]
	v_pk_fma_f32 v[12:13], v[4:5], v[42:43], v[12:13]
	ds_read_b128 v[52:55], v68 offset:28928
	ds_read_b128 v[44:47], v68 offset:12544
	ds_read_b128 v[48:51], v68 offset:20736
	ds_read_b128 v[56:59], v68 offset:37120
	ds_read_b128 v[40:43], v68 offset:4352
	ds_read_b128 v[64:67], v69 offset:80
	s_waitcnt lgkmcnt(7)
	v_pk_mul_f32 v[6:7], v[2:3], v[32:33]
	v_pk_fma_f32 v[6:7], v[4:5], v[34:35], v[6:7]
	v_add_f32_e32 v16, v12, v13
	v_add_f32_e32 v14, v6, v7
	v_pk_mul_f32 v[8:9], v[2:3], v[24:25]
	v_add_f32_dpp v16, v16, v16 quad_perm:[1,0,3,2] row_mask:0xf bank_mask:0xf bound_ctrl:1
	v_add_f32_dpp v14, v14, v14 quad_perm:[1,0,3,2] row_mask:0xf bank_mask:0xf bound_ctrl:1
	v_pk_mul_f32 v[10:11], v[4:5], v[26:27]
	v_add_f32_dpp v16, v16, v16 quad_perm:[2,3,0,1] row_mask:0xf bank_mask:0xf bound_ctrl:1
	v_add_f32_dpp v14, v14, v14 quad_perm:[2,3,0,1] row_mask:0xf bank_mask:0xf bound_ctrl:1
	v_pk_fma_f32 v[8:9], v[28:29], v[60:61], v[8:9] op_sel_hi:[1,0,1]
	v_add_f32_dpp v16, v16, v16 row_half_mirror row_mask:0xf bank_mask:0xf bound_ctrl:1
	v_add_f32_dpp v14, v14, v14 row_half_mirror row_mask:0xf bank_mask:0xf bound_ctrl:1
	v_pk_fma_f32 v[10:11], v[30:31], v[60:61], v[10:11] op_sel_hi:[1,0,1]
	v_add_f32_dpp v16, v16, v16 row_mirror row_mask:0xf bank_mask:0xf bound_ctrl:1
	v_add_f32_dpp v14, v14, v14 row_mirror row_mask:0xf bank_mask:0xf bound_ctrl:1
	ds_write_b32 v70, v16 offset:1920
	v_pk_fma_f32 v[2:3], v[36:37], v[14:15], v[8:9] op_sel_hi:[1,0,1]
	v_pk_fma_f32 v[4:5], v[38:39], v[14:15], v[10:11] op_sel_hi:[1,0,1]
	v_pk_mul_f32 v[12:13], v[2:3], v[20:21]
	v_pk_fma_f32 v[12:13], v[4:5], v[22:23], v[12:13]
	ds_read_b128 v[32:35], v68 offset:29184
	ds_read_b128 v[24:27], v68 offset:12800
	ds_read_b128 v[28:31], v68 offset:20992
	ds_read_b128 v[36:39], v68 offset:37376
	ds_read_b128 v[20:23], v68 offset:4608
	s_waitcnt lgkmcnt(7)
	v_pk_mul_f32 v[6:7], v[2:3], v[52:53]
	v_pk_fma_f32 v[6:7], v[4:5], v[54:55], v[6:7]
	v_add_f32_e32 v16, v12, v13
	v_add_f32_e32 v14, v6, v7
	v_pk_mul_f32 v[8:9], v[2:3], v[44:45]
	v_add_f32_dpp v16, v16, v16 quad_perm:[1,0,3,2] row_mask:0xf bank_mask:0xf bound_ctrl:1
	v_add_f32_dpp v14, v14, v14 quad_perm:[1,0,3,2] row_mask:0xf bank_mask:0xf bound_ctrl:1
	v_pk_mul_f32 v[10:11], v[4:5], v[46:47]
	v_add_f32_dpp v16, v16, v16 quad_perm:[2,3,0,1] row_mask:0xf bank_mask:0xf bound_ctrl:1
	v_add_f32_dpp v14, v14, v14 quad_perm:[2,3,0,1] row_mask:0xf bank_mask:0xf bound_ctrl:1
	v_pk_fma_f32 v[8:9], v[48:49], v[60:61], v[8:9] op_sel:[0,1,0] op_sel_hi:[1,1,1]
	v_add_f32_dpp v16, v16, v16 row_half_mirror row_mask:0xf bank_mask:0xf bound_ctrl:1
	v_add_f32_dpp v14, v14, v14 row_half_mirror row_mask:0xf bank_mask:0xf bound_ctrl:1
	v_pk_fma_f32 v[10:11], v[50:51], v[60:61], v[10:11] op_sel:[0,1,0] op_sel_hi:[1,1,1]
	v_add_f32_dpp v16, v16, v16 row_mirror row_mask:0xf bank_mask:0xf bound_ctrl:1
	v_add_f32_dpp v14, v14, v14 row_mirror row_mask:0xf bank_mask:0xf bound_ctrl:1
	ds_write_b32 v70, v16 offset:2048
	v_pk_fma_f32 v[2:3], v[56:57], v[14:15], v[8:9] op_sel_hi:[1,0,1]
	v_pk_fma_f32 v[4:5], v[58:59], v[14:15], v[10:11] op_sel_hi:[1,0,1]
	v_pk_mul_f32 v[12:13], v[2:3], v[40:41]
	v_pk_fma_f32 v[12:13], v[4:5], v[42:43], v[12:13]
	ds_read_b128 v[52:55], v68 offset:29440
	ds_read_b128 v[44:47], v68 offset:13056
	ds_read_b128 v[48:51], v68 offset:21248
	ds_read_b128 v[56:59], v68 offset:37632
	ds_read_b128 v[40:43], v68 offset:4864
	s_waitcnt lgkmcnt(6)
	v_pk_mul_f32 v[6:7], v[2:3], v[32:33]
	v_pk_fma_f32 v[6:7], v[4:5], v[34:35], v[6:7]
	v_add_f32_e32 v16, v12, v13
	v_add_f32_e32 v14, v6, v7
	v_pk_mul_f32 v[8:9], v[2:3], v[24:25]
	v_add_f32_dpp v16, v16, v16 quad_perm:[1,0,3,2] row_mask:0xf bank_mask:0xf bound_ctrl:1
	v_add_f32_dpp v14, v14, v14 quad_perm:[1,0,3,2] row_mask:0xf bank_mask:0xf bound_ctrl:1
	v_pk_mul_f32 v[10:11], v[4:5], v[26:27]
	v_add_f32_dpp v16, v16, v16 quad_perm:[2,3,0,1] row_mask:0xf bank_mask:0xf bound_ctrl:1
	v_add_f32_dpp v14, v14, v14 quad_perm:[2,3,0,1] row_mask:0xf bank_mask:0xf bound_ctrl:1
	v_pk_fma_f32 v[8:9], v[28:29], v[62:63], v[8:9] op_sel_hi:[1,0,1]
	v_add_f32_dpp v16, v16, v16 row_half_mirror row_mask:0xf bank_mask:0xf bound_ctrl:1
	v_add_f32_dpp v14, v14, v14 row_half_mirror row_mask:0xf bank_mask:0xf bound_ctrl:1
	v_pk_fma_f32 v[10:11], v[30:31], v[62:63], v[10:11] op_sel_hi:[1,0,1]
	v_add_f32_dpp v16, v16, v16 row_mirror row_mask:0xf bank_mask:0xf bound_ctrl:1
	v_add_f32_dpp v14, v14, v14 row_mirror row_mask:0xf bank_mask:0xf bound_ctrl:1
	ds_write_b32 v70, v16 offset:2176
	v_pk_fma_f32 v[2:3], v[36:37], v[14:15], v[8:9] op_sel_hi:[1,0,1]
	v_pk_fma_f32 v[4:5], v[38:39], v[14:15], v[10:11] op_sel_hi:[1,0,1]
	v_pk_mul_f32 v[12:13], v[2:3], v[20:21]
	v_pk_fma_f32 v[12:13], v[4:5], v[22:23], v[12:13]
	ds_read_b128 v[32:35], v68 offset:29696
	ds_read_b128 v[24:27], v68 offset:13312
	ds_read_b128 v[28:31], v68 offset:21504
	ds_read_b128 v[36:39], v68 offset:37888
	ds_read_b128 v[20:23], v68 offset:5120
	s_waitcnt lgkmcnt(6)
; __device__ __forceinline__ void rwkv_scan_phase(Frame& F, const bf16* RKV, const float* WAG, const bf16* AGB, const float* k_k, const float* k_a, const float* r_k, bf16* Y, float* BS, float* ST2) {
;     ...
;                 f32x2 r0[4], w0[4], k0[4], a0[4], b0[4], r1[4], w1[4], k1[4], a1[4], b1[4]; float v0, v1;
;                 SC_LOAD(r0, w0, k0, a0, b0, v0, 0);
; #pragma unroll
;                 for (int t = 0; t < SC_T; t += 2) {
;                     SC_LOAD(r1, w1, k1, a1, b1, v1, t + 1);
;                     SC_STEP(r0, w0, k0, a0, b0, v0, t);
;                     if (t + 2 < SC_T) SC_LOAD(r0, w0, k0, a0, b0, v0, t + 2);
;                     SC_STEP(r1, w1, k1, a1, b1, v1, t + 1);
;                 }
	v_pk_mul_f32 v[6:7], v[2:3], v[52:53]
	v_pk_fma_f32 v[6:7], v[4:5], v[54:55], v[6:7]
	v_add_f32_e32 v16, v12, v13
	v_add_f32_e32 v14, v6, v7
	v_pk_mul_f32 v[8:9], v[2:3], v[44:45]
	v_add_f32_dpp v16, v16, v16 quad_perm:[1,0,3,2] row_mask:0xf bank_mask:0xf bound_ctrl:1
	v_add_f32_dpp v14, v14, v14 quad_perm:[1,0,3,2] row_mask:0xf bank_mask:0xf bound_ctrl:1
	v_pk_mul_f32 v[10:11], v[4:5], v[46:47]
	v_add_f32_dpp v16, v16, v16 quad_perm:[2,3,0,1] row_mask:0xf bank_mask:0xf bound_ctrl:1
	v_add_f32_dpp v14, v14, v14 quad_perm:[2,3,0,1] row_mask:0xf bank_mask:0xf bound_ctrl:1
	v_pk_fma_f32 v[8:9], v[48:49], v[62:63], v[8:9] op_sel:[0,1,0] op_sel_hi:[1,1,1]
	v_add_f32_dpp v16, v16, v16 row_half_mirror row_mask:0xf bank_mask:0xf bound_ctrl:1
	v_add_f32_dpp v14, v14, v14 row_half_mirror row_mask:0xf bank_mask:0xf bound_ctrl:1
	v_pk_fma_f32 v[10:11], v[50:51], v[62:63], v[10:11] op_sel:[0,1,0] op_sel_hi:[1,1,1]
	v_add_f32_dpp v16, v16, v16 row_mirror row_mask:0xf bank_mask:0xf bound_ctrl:1
	v_add_f32_dpp v14, v14, v14 row_mirror row_mask:0xf bank_mask:0xf bound_ctrl:1
	ds_write_b32 v70, v16 offset:2304
	v_pk_fma_f32 v[2:3], v[56:57], v[14:15], v[8:9] op_sel_hi:[1,0,1]
	v_pk_fma_f32 v[4:5], v[58:59], v[14:15], v[10:11] op_sel_hi:[1,0,1]
	v_pk_mul_f32 v[12:13], v[2:3], v[40:41]
	v_pk_fma_f32 v[12:13], v[4:5], v[42:43], v[12:13]
	ds_read_b128 v[52:55], v68 offset:29952
	ds_read_b128 v[44:47], v68 offset:13568
	ds_read_b128 v[48:51], v68 offset:21760
	ds_read_b128 v[56:59], v68 offset:38144
	ds_read_b128 v[40:43], v68 offset:5376
	ds_read_b128 v[60:63], v69 offset:96
	s_waitcnt lgkmcnt(7)
	v_pk_mul_f32 v[6:7], v[2:3], v[32:33]
	v_pk_fma_f32 v[6:7], v[4:5], v[34:35], v[6:7]
	v_add_f32_e32 v16, v12, v13
	v_add_f32_e32 v14, v6, v7
	v_pk_mul_f32 v[8:9], v[2:3], v[24:25]
	v_add_f32_dpp v16, v16, v16 quad_perm:[1,0,3,2] row_mask:0xf bank_mask:0xf bound_ctrl:1
	v_add_f32_dpp v14, v14, v14 quad_perm:[1,0,3,2] row_mask:0xf bank_mask:0xf bound_ctrl:1
	v_pk_mul_f32 v[10:11], v[4:5], v[26:27]
	v_add_f32_dpp v16, v16, v16 quad_perm:[2,3,0,1] row_mask:0xf bank_mask:0xf bound_ctrl:1
	v_add_f32_dpp v14, v14, v14 quad_perm:[2,3,0,1] row_mask:0xf bank_mask:0xf bound_ctrl:1
	v_pk_fma_f32 v[8:9], v[28:29], v[64:65], v[8:9] op_sel_hi:[1,0,1]
	v_add_f32_dpp v16, v16, v16 row_half_mirror row_mask:0xf bank_mask:0xf bound_ctrl:1
	v_add_f32_dpp v14, v14, v14 row_half_mirror row_mask:0xf bank_mask:0xf bound_ctrl:1
	v_pk_fma_f32 v[10:11], v[30:31], v[64:65], v[10:11] op_sel_hi:[1,0,1]
	v_add_f32_dpp v16, v16, v16 row_mirror row_mask:0xf bank_mask:0xf bound_ctrl:1
	v_add_f32_dpp v14, v14, v14 row_mirror row_mask:0xf bank_mask:0xf bound_ctrl:1
	ds_write_b32 v70, v16 offset:2432
	v_pk_fma_f32 v[2:3], v[36:37], v[14:15], v[8:9] op_sel_hi:[1,0,1]
	v_pk_fma_f32 v[4:5], v[38:39], v[14:15], v[10:11] op_sel_hi:[1,0,1]
	v_pk_mul_f32 v[12:13], v[2:3], v[20:21]
	v_pk_fma_f32 v[12:13], v[4:5], v[22:23], v[12:13]
	ds_read_b128 v[32:35], v68 offset:30208
	ds_read_b128 v[24:27], v68 offset:13824
	ds_read_b128 v[28:31], v68 offset:22016
	ds_read_b128 v[36:39], v68 offset:38400
	ds_read_b128 v[20:23], v68 offset:5632
	s_waitcnt lgkmcnt(7)
	v_pk_mul_f32 v[6:7], v[2:3], v[52:53]
	v_pk_fma_f32 v[6:7], v[4:5], v[54:55], v[6:7]
	v_add_f32_e32 v16, v12, v13
	v_add_f32_e32 v14, v6, v7
	v_pk_mul_f32 v[8:9], v[2:3], v[44:45]
	v_add_f32_dpp v16, v16, v16 quad_perm:[1,0,3,2] row_mask:0xf bank_mask:0xf bound_ctrl:1
	v_add_f32_dpp v14, v14, v14 quad_perm:[1,0,3,2] row_mask:0xf bank_mask:0xf bound_ctrl:1
	v_pk_mul_f32 v[10:11], v[4:5], v[46:47]
	v_add_f32_dpp v16, v16, v16 quad_perm:[2,3,0,1] row_mask:0xf bank_mask:0xf bound_ctrl:1
	v_add_f32_dpp v14, v14, v14 quad_perm:[2,3,0,1] row_mask:0xf bank_mask:0xf bound_ctrl:1
	v_pk_fma_f32 v[8:9], v[48:49], v[64:65], v[8:9] op_sel:[0,1,0] op_sel_hi:[1,1,1]
	v_add_f32_dpp v16, v16, v16 row_half_mirror row_mask:0xf bank_mask:0xf bound_ctrl:1
	v_add_f32_dpp v14, v14, v14 row_half_mirror row_mask:0xf bank_mask:0xf bound_ctrl:1
	v_pk_fma_f32 v[10:11], v[50:51], v[64:65], v[10:11] op_sel:[0,1,0] op_sel_hi:[1,1,1]
	v_add_f32_dpp v16, v16, v16 row_mirror row_mask:0xf bank_mask:0xf bound_ctrl:1
	v_add_f32_dpp v14, v14, v14 row_mirror row_mask:0xf bank_mask:0xf bound_ctrl:1
	ds_write_b32 v70, v16 offset:2560
	v_pk_fma_f32 v[2:3], v[56:57], v[14:15], v[8:9] op_sel_hi:[1,0,1]
	v_pk_fma_f32 v[4:5], v[58:59], v[14:15], v[10:11] op_sel_hi:[1,0,1]
	v_pk_mul_f32 v[12:13], v[2:3], v[40:41]
	v_pk_fma_f32 v[12:13], v[4:5], v[42:43], v[12:13]
	ds_read_b128 v[52:55], v68 offset:30464
	ds_read_b128 v[44:47], v68 offset:14080
	ds_read_b128 v[48:51], v68 offset:22272
	ds_read_b128 v[56:59], v68 offset:38656
	ds_read_b128 v[40:43], v68 offset:5888
	s_waitcnt lgkmcnt(6)
	v_pk_mul_f32 v[6:7], v[2:3], v[32:33]
	v_pk_fma_f32 v[6:7], v[4:5], v[34:35], v[6:7]
	v_add_f32_e32 v16, v12, v13
	v_add_f32_e32 v14, v6, v7
	v_pk_mul_f32 v[8:9], v[2:3], v[24:25]
	v_add_f32_dpp v16, v16, v16 quad_perm:[1,0,3,2] row_mask:0xf bank_mask:0xf bound_ctrl:1
	v_add_f32_dpp v14, v14, v14 quad_perm:[1,0,3,2] row_mask:0xf bank_mask:0xf bound_ctrl:1
	v_pk_mul_f32 v[10:11], v[4:5], v[26:27]
	v_add_f32_dpp v16, v16, v16 quad_perm:[2,3,0,1] row_mask:0xf bank_mask:0xf bound_ctrl:1
	v_add_f32_dpp v14, v14, v14 quad_perm:[2,3,0,1] row_mask:0xf bank_mask:0xf bound_ctrl:1
	v_pk_fma_f32 v[8:9], v[28:29], v[66:67], v[8:9] op_sel_hi:[1,0,1]
	v_add_f32_dpp v16, v16, v16 row_half_mirror row_mask:0xf bank_mask:0xf bound_ctrl:1
	v_add_f32_dpp v14, v14, v14 row_half_mirror row_mask:0xf bank_mask:0xf bound_ctrl:1
	v_pk_fma_f32 v[10:11], v[30:31], v[66:67], v[10:11] op_sel_hi:[1,0,1]
	v_add_f32_dpp v16, v16, v16 row_mirror row_mask:0xf bank_mask:0xf bound_ctrl:1
	v_add_f32_dpp v14, v14, v14 row_mirror row_mask:0xf bank_mask:0xf bound_ctrl:1
	ds_write_b32 v70, v16 offset:2688
	v_pk_fma_f32 v[2:3], v[36:37], v[14:15], v[8:9] op_sel_hi:[1,0,1]
	v_pk_fma_f32 v[4:5], v[38:39], v[14:15], v[10:11] op_sel_hi:[1,0,1]
	v_pk_mul_f32 v[12:13], v[2:3], v[20:21]
	v_pk_fma_f32 v[12:13], v[4:5], v[22:23], v[12:13]
	ds_read_b128 v[32:35], v68 offset:30720
	ds_read_b128 v[24:27], v68 offset:14336
	ds_read_b128 v[28:31], v68 offset:22528
	ds_read_b128 v[36:39], v68 offset:38912
	ds_read_b128 v[20:23], v68 offset:6144
	s_waitcnt lgkmcnt(6)
; __device__ __forceinline__ void rwkv_scan_phase(Frame& F, const bf16* RKV, const float* WAG, const bf16* AGB, const float* k_k, const float* k_a, const float* r_k, bf16* Y, float* BS, float* ST2) {
;     ...
;                 f32x2 r0[4], w0[4], k0[4], a0[4], b0[4], r1[4], w1[4], k1[4], a1[4], b1[4]; float v0, v1;
;                 SC_LOAD(r0, w0, k0, a0, b0, v0, 0);
; #pragma unroll
;                 for (int t = 0; t < SC_T; t += 2) {
;                     SC_LOAD(r1, w1, k1, a1, b1, v1, t + 1);
;                     SC_STEP(r0, w0, k0, a0, b0, v0, t);
;                     if (t + 2 < SC_T) SC_LOAD(r0, w0, k0, a0, b0, v0, t + 2);
;                     SC_STEP(r1, w1, k1, a1, b1, v1, t + 1);
;                 }
	v_pk_mul_f32 v[6:7], v[2:3], v[52:53]
	v_pk_fma_f32 v[6:7], v[4:5], v[54:55], v[6:7]
	v_add_f32_e32 v16, v12, v13
	v_add_f32_e32 v14, v6, v7
	v_pk_mul_f32 v[8:9], v[2:3], v[44:45]
	v_add_f32_dpp v16, v16, v16 quad_perm:[1,0,3,2] row_mask:0xf bank_mask:0xf bound_ctrl:1
	v_add_f32_dpp v14, v14, v14 quad_perm:[1,0,3,2] row_mask:0xf bank_mask:0xf bound_ctrl:1
	v_pk_mul_f32 v[10:11], v[4:5], v[46:47]
	v_add_f32_dpp v16, v16, v16 quad_perm:[2,3,0,1] row_mask:0xf bank_mask:0xf bound_ctrl:1
	v_add_f32_dpp v14, v14, v14 quad_perm:[2,3,0,1] row_mask:0xf bank_mask:0xf bound_ctrl:1
	v_pk_fma_f32 v[8:9], v[48:49], v[66:67], v[8:9] op_sel:[0,1,0] op_sel_hi:[1,1,1]
	v_add_f32_dpp v16, v16, v16 row_half_mirror row_mask:0xf bank_mask:0xf bound_ctrl:1
	v_add_f32_dpp v14, v14, v14 row_half_mirror row_mask:0xf bank_mask:0xf bound_ctrl:1
	v_pk_fma_f32 v[10:11], v[50:51], v[66:67], v[10:11] op_sel:[0,1,0] op_sel_hi:[1,1,1]
	v_add_f32_dpp v16, v16, v16 row_mirror row_mask:0xf bank_mask:0xf bound_ctrl:1
	v_add_f32_dpp v14, v14, v14 row_mirror row_mask:0xf bank_mask:0xf bound_ctrl:1
	ds_write_b32 v70, v16 offset:2816
	v_pk_fma_f32 v[2:3], v[56:57], v[14:15], v[8:9] op_sel_hi:[1,0,1]
	v_pk_fma_f32 v[4:5], v[58:59], v[14:15], v[10:11] op_sel_hi:[1,0,1]
	v_pk_mul_f32 v[12:13], v[2:3], v[40:41]
	v_pk_fma_f32 v[12:13], v[4:5], v[42:43], v[12:13]
	ds_read_b128 v[52:55], v68 offset:30976
	ds_read_b128 v[44:47], v68 offset:14592
	ds_read_b128 v[48:51], v68 offset:22784
	ds_read_b128 v[56:59], v68 offset:39168
	ds_read_b128 v[40:43], v68 offset:6400
	ds_read_b128 v[64:67], v69 offset:112
	s_waitcnt lgkmcnt(7)
	v_pk_mul_f32 v[6:7], v[2:3], v[32:33]
	v_pk_fma_f32 v[6:7], v[4:5], v[34:35], v[6:7]
	v_add_f32_e32 v16, v12, v13
	v_add_f32_e32 v14, v6, v7
	v_pk_mul_f32 v[8:9], v[2:3], v[24:25]
	v_add_f32_dpp v16, v16, v16 quad_perm:[1,0,3,2] row_mask:0xf bank_mask:0xf bound_ctrl:1
	v_add_f32_dpp v14, v14, v14 quad_perm:[1,0,3,2] row_mask:0xf bank_mask:0xf bound_ctrl:1
	v_pk_mul_f32 v[10:11], v[4:5], v[26:27]
	v_add_f32_dpp v16, v16, v16 quad_perm:[2,3,0,1] row_mask:0xf bank_mask:0xf bound_ctrl:1
	v_add_f32_dpp v14, v14, v14 quad_perm:[2,3,0,1] row_mask:0xf bank_mask:0xf bound_ctrl:1
	v_pk_fma_f32 v[8:9], v[28:29], v[60:61], v[8:9] op_sel_hi:[1,0,1]
	v_add_f32_dpp v16, v16, v16 row_half_mirror row_mask:0xf bank_mask:0xf bound_ctrl:1
	v_add_f32_dpp v14, v14, v14 row_half_mirror row_mask:0xf bank_mask:0xf bound_ctrl:1
	v_pk_fma_f32 v[10:11], v[30:31], v[60:61], v[10:11] op_sel_hi:[1,0,1]
	v_add_f32_dpp v16, v16, v16 row_mirror row_mask:0xf bank_mask:0xf bound_ctrl:1
	v_add_f32_dpp v14, v14, v14 row_mirror row_mask:0xf bank_mask:0xf bound_ctrl:1
	ds_write_b32 v70, v16 offset:2944
	v_pk_fma_f32 v[2:3], v[36:37], v[14:15], v[8:9] op_sel_hi:[1,0,1]
	v_pk_fma_f32 v[4:5], v[38:39], v[14:15], v[10:11] op_sel_hi:[1,0,1]
	v_pk_mul_f32 v[12:13], v[2:3], v[20:21]
	v_pk_fma_f32 v[12:13], v[4:5], v[22:23], v[12:13]
	ds_read_b128 v[32:35], v68 offset:31232
	ds_read_b128 v[24:27], v68 offset:14848
	ds_read_b128 v[28:31], v68 offset:23040
	ds_read_b128 v[36:39], v68 offset:39424
	ds_read_b128 v[20:23], v68 offset:6656
	s_waitcnt lgkmcnt(7)
	v_pk_mul_f32 v[6:7], v[2:3], v[52:53]
	v_pk_fma_f32 v[6:7], v[4:5], v[54:55], v[6:7]
	v_add_f32_e32 v16, v12, v13
	v_add_f32_e32 v14, v6, v7
	v_pk_mul_f32 v[8:9], v[2:3], v[44:45]
	v_add_f32_dpp v16, v16, v16 quad_perm:[1,0,3,2] row_mask:0xf bank_mask:0xf bound_ctrl:1
	v_add_f32_dpp v14, v14, v14 quad_perm:[1,0,3,2] row_mask:0xf bank_mask:0xf bound_ctrl:1
	v_pk_mul_f32 v[10:11], v[4:5], v[46:47]
	v_add_f32_dpp v16, v16, v16 quad_perm:[2,3,0,1] row_mask:0xf bank_mask:0xf bound_ctrl:1
	v_add_f32_dpp v14, v14, v14 quad_perm:[2,3,0,1] row_mask:0xf bank_mask:0xf bound_ctrl:1
	v_pk_fma_f32 v[8:9], v[48:49], v[60:61], v[8:9] op_sel:[0,1,0] op_sel_hi:[1,1,1]
	v_add_f32_dpp v16, v16, v16 row_half_mirror row_mask:0xf bank_mask:0xf bound_ctrl:1
	v_add_f32_dpp v14, v14, v14 row_half_mirror row_mask:0xf bank_mask:0xf bound_ctrl:1
	v_pk_fma_f32 v[10:11], v[50:51], v[60:61], v[10:11] op_sel:[0,1,0] op_sel_hi:[1,1,1]
	v_add_f32_dpp v16, v16, v16 row_mirror row_mask:0xf bank_mask:0xf bound_ctrl:1
	v_add_f32_dpp v14, v14, v14 row_mirror row_mask:0xf bank_mask:0xf bound_ctrl:1
	ds_write_b32 v70, v16 offset:3072
	v_pk_fma_f32 v[2:3], v[56:57], v[14:15], v[8:9] op_sel_hi:[1,0,1]
	v_pk_fma_f32 v[4:5], v[58:59], v[14:15], v[10:11] op_sel_hi:[1,0,1]
	v_pk_mul_f32 v[12:13], v[2:3], v[40:41]
	v_pk_fma_f32 v[12:13], v[4:5], v[42:43], v[12:13]
	ds_read_b128 v[52:55], v68 offset:31488
	ds_read_b128 v[44:47], v68 offset:15104
	ds_read_b128 v[48:51], v68 offset:23296
	ds_read_b128 v[56:59], v68 offset:39680
	ds_read_b128 v[40:43], v68 offset:6912
	s_waitcnt lgkmcnt(6)
	v_pk_mul_f32 v[6:7], v[2:3], v[32:33]
	v_pk_fma_f32 v[6:7], v[4:5], v[34:35], v[6:7]
	v_add_f32_e32 v16, v12, v13
	v_add_f32_e32 v14, v6, v7
	v_pk_mul_f32 v[8:9], v[2:3], v[24:25]
	v_add_f32_dpp v16, v16, v16 quad_perm:[1,0,3,2] row_mask:0xf bank_mask:0xf bound_ctrl:1
	v_add_f32_dpp v14, v14, v14 quad_perm:[1,0,3,2] row_mask:0xf bank_mask:0xf bound_ctrl:1
	v_pk_mul_f32 v[10:11], v[4:5], v[26:27]
	v_add_f32_dpp v16, v16, v16 quad_perm:[2,3,0,1] row_mask:0xf bank_mask:0xf bound_ctrl:1
	v_add_f32_dpp v14, v14, v14 quad_perm:[2,3,0,1] row_mask:0xf bank_mask:0xf bound_ctrl:1
	v_pk_fma_f32 v[8:9], v[28:29], v[62:63], v[8:9] op_sel_hi:[1,0,1]
	v_add_f32_dpp v16, v16, v16 row_half_mirror row_mask:0xf bank_mask:0xf bound_ctrl:1
	v_add_f32_dpp v14, v14, v14 row_half_mirror row_mask:0xf bank_mask:0xf bound_ctrl:1
	v_pk_fma_f32 v[10:11], v[30:31], v[62:63], v[10:11] op_sel_hi:[1,0,1]
	v_add_f32_dpp v16, v16, v16 row_mirror row_mask:0xf bank_mask:0xf bound_ctrl:1
	v_add_f32_dpp v14, v14, v14 row_mirror row_mask:0xf bank_mask:0xf bound_ctrl:1
	ds_write_b32 v70, v16 offset:3200
	v_pk_fma_f32 v[2:3], v[36:37], v[14:15], v[8:9] op_sel_hi:[1,0,1]
	v_pk_fma_f32 v[4:5], v[38:39], v[14:15], v[10:11] op_sel_hi:[1,0,1]
	v_pk_mul_f32 v[12:13], v[2:3], v[20:21]
	v_pk_fma_f32 v[12:13], v[4:5], v[22:23], v[12:13]
	ds_read_b128 v[32:35], v68 offset:31744
	ds_read_b128 v[24:27], v68 offset:15360
	ds_read_b128 v[28:31], v68 offset:23552
	ds_read_b128 v[36:39], v68 offset:39936
	ds_read_b128 v[20:23], v68 offset:7168
	s_waitcnt lgkmcnt(6)
; __device__ __forceinline__ void rwkv_scan_phase(Frame& F, const bf16* RKV, const float* WAG, const bf16* AGB, const float* k_k, const float* k_a, const float* r_k, bf16* Y, float* BS, float* ST2) {
;     ...
;                 f32x2 r0[4], w0[4], k0[4], a0[4], b0[4], r1[4], w1[4], k1[4], a1[4], b1[4]; float v0, v1;
;                 SC_LOAD(r0, w0, k0, a0, b0, v0, 0);
; #pragma unroll
;                 for (int t = 0; t < SC_T; t += 2) {
;                     SC_LOAD(r1, w1, k1, a1, b1, v1, t + 1);
;                     SC_STEP(r0, w0, k0, a0, b0, v0, t);
;                     if (t + 2 < SC_T) SC_LOAD(r0, w0, k0, a0, b0, v0, t + 2);
;                     SC_STEP(r1, w1, k1, a1, b1, v1, t + 1);
;                 }
	v_pk_mul_f32 v[6:7], v[2:3], v[52:53]
	v_pk_fma_f32 v[6:7], v[4:5], v[54:55], v[6:7]
	v_add_f32_e32 v16, v12, v13
	v_add_f32_e32 v14, v6, v7
	v_pk_mul_f32 v[8:9], v[2:3], v[44:45]
	v_add_f32_dpp v16, v16, v16 quad_perm:[1,0,3,2] row_mask:0xf bank_mask:0xf bound_ctrl:1
	v_add_f32_dpp v14, v14, v14 quad_perm:[1,0,3,2] row_mask:0xf bank_mask:0xf bound_ctrl:1
	v_pk_mul_f32 v[10:11], v[4:5], v[46:47]
	v_add_f32_dpp v16, v16, v16 quad_perm:[2,3,0,1] row_mask:0xf bank_mask:0xf bound_ctrl:1
	v_add_f32_dpp v14, v14, v14 quad_perm:[2,3,0,1] row_mask:0xf bank_mask:0xf bound_ctrl:1
	v_pk_fma_f32 v[8:9], v[48:49], v[62:63], v[8:9] op_sel:[0,1,0] op_sel_hi:[1,1,1]
	v_add_f32_dpp v16, v16, v16 row_half_mirror row_mask:0xf bank_mask:0xf bound_ctrl:1
	v_add_f32_dpp v14, v14, v14 row_half_mirror row_mask:0xf bank_mask:0xf bound_ctrl:1
	v_pk_fma_f32 v[10:11], v[50:51], v[62:63], v[10:11] op_sel:[0,1,0] op_sel_hi:[1,1,1]
	v_add_f32_dpp v16, v16, v16 row_mirror row_mask:0xf bank_mask:0xf bound_ctrl:1
	v_add_f32_dpp v14, v14, v14 row_mirror row_mask:0xf bank_mask:0xf bound_ctrl:1
	ds_write_b32 v70, v16 offset:3328
	v_pk_fma_f32 v[2:3], v[56:57], v[14:15], v[8:9] op_sel_hi:[1,0,1]
	v_pk_fma_f32 v[4:5], v[58:59], v[14:15], v[10:11] op_sel_hi:[1,0,1]
	v_pk_mul_f32 v[12:13], v[2:3], v[40:41]
	v_pk_fma_f32 v[12:13], v[4:5], v[42:43], v[12:13]
	ds_read_b128 v[52:55], v68 offset:32000
	ds_read_b128 v[44:47], v68 offset:15616
	ds_read_b128 v[48:51], v68 offset:23808
	ds_read_b128 v[56:59], v68 offset:40192
	ds_read_b128 v[40:43], v68 offset:7424
	s_waitcnt lgkmcnt(6)
	v_pk_mul_f32 v[6:7], v[2:3], v[32:33]
	v_pk_fma_f32 v[6:7], v[4:5], v[34:35], v[6:7]
	v_add_f32_e32 v16, v12, v13
	v_add_f32_e32 v14, v6, v7
	v_pk_mul_f32 v[8:9], v[2:3], v[24:25]
	v_add_f32_dpp v16, v16, v16 quad_perm:[1,0,3,2] row_mask:0xf bank_mask:0xf bound_ctrl:1
	v_add_f32_dpp v14, v14, v14 quad_perm:[1,0,3,2] row_mask:0xf bank_mask:0xf bound_ctrl:1
	v_pk_mul_f32 v[10:11], v[4:5], v[26:27]
	v_add_f32_dpp v16, v16, v16 quad_perm:[2,3,0,1] row_mask:0xf bank_mask:0xf bound_ctrl:1
	v_add_f32_dpp v14, v14, v14 quad_perm:[2,3,0,1] row_mask:0xf bank_mask:0xf bound_ctrl:1
	v_pk_fma_f32 v[8:9], v[28:29], v[64:65], v[8:9] op_sel_hi:[1,0,1]
	v_add_f32_dpp v16, v16, v16 row_half_mirror row_mask:0xf bank_mask:0xf bound_ctrl:1
	v_add_f32_dpp v14, v14, v14 row_half_mirror row_mask:0xf bank_mask:0xf bound_ctrl:1
	v_pk_fma_f32 v[10:11], v[30:31], v[64:65], v[10:11] op_sel_hi:[1,0,1]
	v_add_f32_dpp v16, v16, v16 row_mirror row_mask:0xf bank_mask:0xf bound_ctrl:1
	v_add_f32_dpp v14, v14, v14 row_mirror row_mask:0xf bank_mask:0xf bound_ctrl:1
	ds_write_b32 v70, v16 offset:3456
	v_pk_fma_f32 v[2:3], v[36:37], v[14:15], v[8:9] op_sel_hi:[1,0,1]
	v_pk_fma_f32 v[4:5], v[38:39], v[14:15], v[10:11] op_sel_hi:[1,0,1]
	v_pk_mul_f32 v[12:13], v[2:3], v[20:21]
	v_pk_fma_f32 v[12:13], v[4:5], v[22:23], v[12:13]
	ds_read_b128 v[32:35], v68 offset:32256
	ds_read_b128 v[24:27], v68 offset:15872
	ds_read_b128 v[28:31], v68 offset:24064
	ds_read_b128 v[36:39], v68 offset:40448
	ds_read_b128 v[20:23], v68 offset:7680
	s_waitcnt lgkmcnt(6)
	v_pk_mul_f32 v[6:7], v[2:3], v[52:53]
	v_pk_fma_f32 v[6:7], v[4:5], v[54:55], v[6:7]
	v_add_f32_e32 v16, v12, v13
	v_add_f32_e32 v14, v6, v7
	v_pk_mul_f32 v[8:9], v[2:3], v[44:45]
	v_add_f32_dpp v16, v16, v16 quad_perm:[1,0,3,2] row_mask:0xf bank_mask:0xf bound_ctrl:1
	v_add_f32_dpp v14, v14, v14 quad_perm:[1,0,3,2] row_mask:0xf bank_mask:0xf bound_ctrl:1
	v_pk_mul_f32 v[10:11], v[4:5], v[46:47]
	v_add_f32_dpp v16, v16, v16 quad_perm:[2,3,0,1] row_mask:0xf bank_mask:0xf bound_ctrl:1
	v_add_f32_dpp v14, v14, v14 quad_perm:[2,3,0,1] row_mask:0xf bank_mask:0xf bound_ctrl:1
	v_pk_fma_f32 v[8:9], v[48:49], v[64:65], v[8:9] op_sel:[0,1,0] op_sel_hi:[1,1,1]
	v_add_f32_dpp v16, v16, v16 row_half_mirror row_mask:0xf bank_mask:0xf bound_ctrl:1
	v_add_f32_dpp v14, v14, v14 row_half_mirror row_mask:0xf bank_mask:0xf bound_ctrl:1
	v_pk_fma_f32 v[10:11], v[50:51], v[64:65], v[10:11] op_sel:[0,1,0] op_sel_hi:[1,1,1]
	v_add_f32_dpp v16, v16, v16 row_mirror row_mask:0xf bank_mask:0xf bound_ctrl:1
	v_add_f32_dpp v14, v14, v14 row_mirror row_mask:0xf bank_mask:0xf bound_ctrl:1
	ds_write_b32 v70, v16 offset:3584
	v_pk_fma_f32 v[2:3], v[56:57], v[14:15], v[8:9] op_sel_hi:[1,0,1]
	v_pk_fma_f32 v[4:5], v[58:59], v[14:15], v[10:11] op_sel_hi:[1,0,1]
	v_pk_mul_f32 v[12:13], v[2:3], v[40:41]
	v_pk_fma_f32 v[12:13], v[4:5], v[42:43], v[12:13]
	ds_read_b128 v[52:55], v68 offset:32512
	ds_read_b128 v[44:47], v68 offset:16128
	ds_read_b128 v[48:51], v68 offset:24320
	ds_read_b128 v[56:59], v68 offset:40704
	ds_read_b128 v[40:43], v68 offset:7936
	s_waitcnt lgkmcnt(6)
; __device__ __forceinline__ void rwkv_scan_phase(Frame& F, const bf16* RKV, const float* WAG, const bf16* AGB, const float* k_k, const float* k_a, const float* r_k, bf16* Y, float* BS, float* ST2) {
;     ...
;                 f32x2 r0[4], w0[4], k0[4], a0[4], b0[4], r1[4], w1[4], k1[4], a1[4], b1[4]; float v0, v1;
;                 SC_LOAD(r0, w0, k0, a0, b0, v0, 0);
; #pragma unroll
;                 for (int t = 0; t < SC_T; t += 2) {
;                     SC_LOAD(r1, w1, k1, a1, b1, v1, t + 1);
;                     SC_STEP(r0, w0, k0, a0, b0, v0, t);
;                     if (t + 2 < SC_T) SC_LOAD(r0, w0, k0, a0, b0, v0, t + 2);
;                     SC_STEP(r1, w1, k1, a1, b1, v1, t + 1);
;                 }
;     ...
;                 __syncthreads();
;             }
;         }
;     }
;     __syncthreads();
	v_pk_mul_f32 v[6:7], v[2:3], v[32:33]
	v_pk_fma_f32 v[6:7], v[4:5], v[34:35], v[6:7]
	v_add_f32_e32 v16, v12, v13
	v_add_f32_e32 v14, v6, v7
	v_pk_mul_f32 v[8:9], v[2:3], v[24:25]
	v_add_f32_dpp v16, v16, v16 quad_perm:[1,0,3,2] row_mask:0xf bank_mask:0xf bound_ctrl:1
	v_add_f32_dpp v14, v14, v14 quad_perm:[1,0,3,2] row_mask:0xf bank_mask:0xf bound_ctrl:1
	v_pk_mul_f32 v[10:11], v[4:5], v[26:27]
	v_add_f32_dpp v16, v16, v16 quad_perm:[2,3,0,1] row_mask:0xf bank_mask:0xf bound_ctrl:1
	v_add_f32_dpp v14, v14, v14 quad_perm:[2,3,0,1] row_mask:0xf bank_mask:0xf bound_ctrl:1
	v_pk_fma_f32 v[8:9], v[28:29], v[66:67], v[8:9] op_sel_hi:[1,0,1]
	v_add_f32_dpp v16, v16, v16 row_half_mirror row_mask:0xf bank_mask:0xf bound_ctrl:1
	v_add_f32_dpp v14, v14, v14 row_half_mirror row_mask:0xf bank_mask:0xf bound_ctrl:1
	v_pk_fma_f32 v[10:11], v[30:31], v[66:67], v[10:11] op_sel_hi:[1,0,1]
	v_add_f32_dpp v16, v16, v16 row_mirror row_mask:0xf bank_mask:0xf bound_ctrl:1
	v_add_f32_dpp v14, v14, v14 row_mirror row_mask:0xf bank_mask:0xf bound_ctrl:1
	ds_write_b32 v70, v16 offset:3712
	v_pk_fma_f32 v[2:3], v[36:37], v[14:15], v[8:9] op_sel_hi:[1,0,1]
	v_pk_fma_f32 v[4:5], v[38:39], v[14:15], v[10:11] op_sel_hi:[1,0,1]
	v_pk_mul_f32 v[12:13], v[2:3], v[20:21]
	v_pk_fma_f32 v[12:13], v[4:5], v[22:23], v[12:13]
	s_waitcnt lgkmcnt(1)
	v_pk_mul_f32 v[6:7], v[2:3], v[52:53]
	v_pk_fma_f32 v[6:7], v[4:5], v[54:55], v[6:7]
	v_add_f32_e32 v16, v12, v13
	v_add_f32_e32 v14, v6, v7
	v_pk_mul_f32 v[8:9], v[2:3], v[44:45]
	v_add_f32_dpp v16, v16, v16 quad_perm:[1,0,3,2] row_mask:0xf bank_mask:0xf bound_ctrl:1
	v_add_f32_dpp v14, v14, v14 quad_perm:[1,0,3,2] row_mask:0xf bank_mask:0xf bound_ctrl:1
	v_pk_mul_f32 v[10:11], v[4:5], v[46:47]
	v_add_f32_dpp v16, v16, v16 quad_perm:[2,3,0,1] row_mask:0xf bank_mask:0xf bound_ctrl:1
	v_add_f32_dpp v14, v14, v14 quad_perm:[2,3,0,1] row_mask:0xf bank_mask:0xf bound_ctrl:1
	v_pk_fma_f32 v[8:9], v[48:49], v[66:67], v[8:9] op_sel:[0,1,0] op_sel_hi:[1,1,1]
	v_add_f32_dpp v16, v16, v16 row_half_mirror row_mask:0xf bank_mask:0xf bound_ctrl:1
	v_add_f32_dpp v14, v14, v14 row_half_mirror row_mask:0xf bank_mask:0xf bound_ctrl:1
	v_pk_fma_f32 v[10:11], v[50:51], v[66:67], v[10:11] op_sel:[0,1,0] op_sel_hi:[1,1,1]
	v_add_f32_dpp v16, v16, v16 row_mirror row_mask:0xf bank_mask:0xf bound_ctrl:1
	v_add_f32_dpp v14, v14, v14 row_mirror row_mask:0xf bank_mask:0xf bound_ctrl:1
	ds_write_b32 v70, v16 offset:3840
	v_pk_fma_f32 v[2:3], v[56:57], v[14:15], v[8:9] op_sel_hi:[1,0,1]
	v_pk_fma_f32 v[4:5], v[58:59], v[14:15], v[10:11] op_sel_hi:[1,0,1]
	v_pk_mul_f32 v[12:13], v[2:3], v[40:41]
	v_pk_fma_f32 v[12:13], v[4:5], v[42:43], v[12:13]
	v_add_f32_e32 v16, v12, v13
	s_nop 1
	v_add_f32_dpp v16, v16, v16 quad_perm:[1,0,3,2] row_mask:0xf bank_mask:0xf bound_ctrl:1
	s_nop 1
	v_add_f32_dpp v16, v16, v16 quad_perm:[2,3,0,1] row_mask:0xf bank_mask:0xf bound_ctrl:1
	s_nop 1
	v_add_f32_dpp v16, v16, v16 row_half_mirror row_mask:0xf bank_mask:0xf bound_ctrl:1
	s_nop 1
	v_add_f32_dpp v16, v16, v16 row_mirror row_mask:0xf bank_mask:0xf bound_ctrl:1
	ds_write_b32 v70, v16 offset:3968
	s_waitcnt lgkmcnt(0)
	s_barrier
	s_xor_b32 s38, s38, 0xb400
	s_xor_b32 s39, s39, 0xb400
	s_xor_b32 s40, s40, 0x1000
	s_xor_b32 s41, s41, 0x1000
	s_add_i32 s37, s37, 1
	s_cmp_lt_u32 s37, 64
	s_cbranch_scc1 .Lscan_chunk
	s_cmp_lt_u32 s80, 4
	s_cbranch_scc1 .Lscan_item_next
	v_add_u32_e32 v161, s41, v160
	ds_read_b128 v[164:167], v161
	s_waitcnt lgkmcnt(0)
	v_cvt_pk_bf16_f32 v168, v164, v165
	v_cvt_pk_bf16_f32 v169, v166, v167
	v_add_f32_e32 v170, v164, v165
	v_add_f32_e32 v172, v166, v167
	global_store_dwordx2 v162, v[168:169], s[18:19]
	v_mul_f32_e32 v171, v164, v164
	v_mul_f32_e32 v173, v166, v166
	v_add_f32_e32 v170, v170, v172
	v_fmac_f32_e32 v171, v165, v165
	v_fmac_f32_e32 v173, v167, v167
	v_add_f32_dpp v170, v170, v170 quad_perm:[1,0,3,2] row_mask:0xf bank_mask:0xf bound_ctrl:1
	v_add_f32_e32 v171, v171, v173
	s_nop 0
	v_add_f32_dpp v170, v170, v170 quad_perm:[2,3,0,1] row_mask:0xf bank_mask:0xf bound_ctrl:1
	v_add_f32_dpp v171, v171, v171 quad_perm:[1,0,3,2] row_mask:0xf bank_mask:0xf bound_ctrl:1
	s_nop 0
	v_add_f32_dpp v170, v170, v170 row_half_mirror row_mask:0xf bank_mask:0xf bound_ctrl:1
	v_add_f32_dpp v171, v171, v171 quad_perm:[2,3,0,1] row_mask:0xf bank_mask:0xf bound_ctrl:1
	s_nop 1
	v_add_f32_dpp v171, v171, v171 row_half_mirror row_mask:0xf bank_mask:0xf bound_ctrl:1
	s_mov_b64 exec, s[46:47]
	s_nop 1
	global_store_dwordx2 v163, v[170:171], s[20:21]
	s_mov_b64 exec, -1
	s_nop 1
.Lscan_item_next:
	s_add_i32 s33, s33, s52
	s_cmpk_lt_i32 s33, 0x100
	s_cbranch_scc1 .Lscan_item
	s_branch .LBB0_1814
